# nt policy on the f32 residual-stream X stores of the out-proj and down-proj epilogues (bf16 XB stores stay default)
# baseline (speedup 1.0000x reference)
; DI void ss_add(ssacc_t* p, float v) { atomicAdd(p, (ssacc_t)__float2ull_rn(v * 4294967296.f)); }
; DI float ss_get(const ssacc_t* p) { const ssacc_t v = *p; return (float)(unsigned)(v >> 32) + (float)(unsigned)(v & 0xffffffffull) * 2.3283064365386963e-10f; }
; DI float quad_sum(float s) { s += __shfl_xor(s, 16); s += __shfl_xor(s, 32); return s; }
; DI float sq8(const f32x4& a, const f32x4& b) { return (a[0] * a[0] + a[1] * a[1]) + (a[2] * a[2] + a[3] * a[3]) + (b[0] * b[0] + b[1] * b[1]) + (b[2] * b[2] + b[3] * b[3]); }
; DI u32x4 pack8(const f32x4& a, const f32x4& b) { u32x4 w; w.x = cvtpk(a[0], a[1]); w.y = cvtpk(a[2], a[3]); w.z = cvtpk(b[0], b[1]); w.w = cvtpk(b[2], b[3]); return w; }
;     DI void operator()(const Acc& acc, const Unit& u, int wr, int wc, int fr, int fq) const {
;     ...
;             for (int m = 0; m < 4; ++m) {
;                 asm volatile("" ::: "memory");
;                 const int row = u.pm * 256 + ai * 128 + wr * 64 + m * 16 + fr;
;                 const float rs = rsqrtf(ss_get(ss_dil + row) * (1.f / 512.f) + EPS_);
;                 float sq = 0.f;
; #pragma unroll
;                 for (int bj = 0; bj < 2; ++bj) {
;                     const size_t off = (size_t)row * 2048 + u.pn * 256 + bj * 128 + wc * 32 + 8 * fq;
;                     const f32x4 v0 = *(const f32x4*)(xin + off) + acc[ai][bj][m][0] * rs, v1 = *(const f32x4*)(xin + off + 4) + acc[ai][bj][m][1] * rs;
;                     *(f32x4*)(X + off) = v0; *(f32x4*)(X + off + 4) = v1; *(u32x4*)(XB + off) = pack8(v0, v1); sq += sq8(v0, v1);
;                 }
;                 sq = quad_sum(sq); if (fq == 0) ss_add(ssx1 + row, sq);
.LBB0_1278:
	v_lshl_add_u32 v146, s41, 8, v141
	v_ashrrev_i32_e32 v147, 31, v146
	v_lshl_add_u64 v[148:149], v[146:147], 3, s[56:57]
	global_load_dwordx2 v[208:209], v[148:149], off
	global_load_dwordx2 v[210:211], v[148:149], off offset:128
	global_load_dwordx2 v[212:213], v[148:149], off offset:256
	global_load_dwordx2 v[214:215], v[148:149], off offset:384
	global_load_dwordx2 v[216:217], v[148:149], off offset:1024
	global_load_dwordx2 v[218:219], v[148:149], off offset:1152
	global_load_dwordx2 v[220:221], v[148:149], off offset:1280
	global_load_dwordx2 v[222:223], v[148:149], off offset:1408
	s_min_u32 s16, s88, 32
	s_sub_i32 s17, 32, s16
	s_lshl_b32 s4, s40, 8
	s_ashr_i32 s14, s4, 31
	v_mov_b32_e32 v131, s14
	v_or_b32_e32 v130, s4, v140
	s_waitcnt vmcnt(7)
	v_mov_b32_e32 v148, v208
	v_mov_b32_e32 v149, v209
	v_mov_b32_e32 v128, v149
	v_lshlrev_b64 v[150:151], s16, v[128:129]
	v_min_u32_e32 v128, 1, v150
	v_or_b32_e32 v128, v151, v128
	v_cvt_f32_u32_e32 v128, v128
	v_cvt_f32_u32_e32 v148, v148
	v_ldexp_f32 v128, v128, s17
	v_fmac_f32_e32 v128, 0x2f800000, v148
	v_fmamk_f32 v128, v128, 0x3b000000, v195
	v_cmp_gt_f32_e32 vcc, s27, v128
	v_mul_f32_e32 v148, 0x4b800000, v128
	s_nop 0
	v_cndmask_b32_e32 v128, v128, v148, vcc
	v_rsq_f32_e32 v128, v128
	s_nop 0
	v_mul_f32_e32 v148, 0x45800000, v128
	v_cndmask_b32_e32 v128, v128, v148, vcc
	v_lshlrev_b64 v[148:149], 11, v[146:147]
	v_lshl_add_u64 v[148:149], v[148:149], 0, v[130:131]
	v_lshlrev_b64 v[164:165], 2, v[148:149]
	s_waitcnt lgkmcnt(0)
	v_lshl_add_u64 v[150:151], s[8:9], 0, v[164:165]
	global_load_dwordx4 v[156:159], v[150:151], off offset:16
	global_load_dwordx4 v[160:163], v[150:151], off
	global_load_dwordx4 v[166:169], v[150:151], off offset:528
	global_load_dwordx4 v[170:173], v[150:151], off offset:512
	s_waitcnt vmcnt(3)
	v_pk_fma_f32 v[124:125], v[124:125], v[128:129], v[156:157] op_sel_hi:[1,0,1]
	s_waitcnt vmcnt(2)
	v_pk_fma_f32 v[122:123], v[122:123], v[128:129], v[162:163] op_sel_hi:[1,0,1]
	v_pk_fma_f32 v[120:121], v[120:121], v[128:129], v[160:161] op_sel_hi:[1,0,1]
	v_lshl_add_u64 v[156:157], s[60:61], 0, v[164:165]
	v_pk_fma_f32 v[126:127], v[126:127], v[128:129], v[158:159] op_sel_hi:[1,0,1]
	global_store_dwordx4 v[156:157], v[120:123], off nt
	global_store_dwordx4 v[156:157], v[124:127], off offset:16 nt
	v_cvt_pk_bf16_f32 v156, v120, v121
	v_mul_f32_e32 v121, v121, v121
	v_fmac_f32_e32 v121, v120, v120
	v_mul_f32_e32 v120, v123, v123
	v_fmac_f32_e32 v120, v122, v122
	v_add_f32_e32 v120, v121, v120
	v_mul_f32_e32 v121, v125, v125
	v_fmac_f32_e32 v121, v124, v124
	v_cvt_pk_bf16_f32 v157, v122, v123
	v_cvt_pk_bf16_f32 v158, v124, v125
	v_cvt_pk_bf16_f32 v159, v126, v127
	v_lshl_add_u64 v[160:161], v[148:149], 1, s[62:63]
	v_add_f32_e32 v120, v121, v120
	v_mul_f32_e32 v121, v127, v127
	global_store_dwordx4 v[160:161], v[156:159], off
	v_fmac_f32_e32 v121, v126, v126
	v_add_f32_e32 v155, v121, v120
	v_or_b32_e32 v148, 0x80, v148
	s_waitcnt vmcnt(3)
	v_mov_b32_e32 v120, v166
	v_mov_b32_e32 v121, v167
	v_mov_b32_e32 v122, v168
	v_mov_b32_e32 v123, v169
	v_mov_b32_e32 v124, v170
	v_mov_b32_e32 v125, v171
	v_mov_b32_e32 v126, v172
	v_mov_b32_e32 v127, v173
	v_pk_fma_f32 v[116:117], v[116:117], v[128:129], v[120:121] op_sel_hi:[1,0,1]
	v_pk_fma_f32 v[114:115], v[114:115], v[128:129], v[126:127] op_sel_hi:[1,0,1]
	v_pk_fma_f32 v[112:113], v[112:113], v[128:129], v[124:125] op_sel_hi:[1,0,1]
	v_lshl_add_u64 v[120:121], v[148:149], 2, s[60:61]
	v_pk_fma_f32 v[118:119], v[118:119], v[128:129], v[122:123] op_sel_hi:[1,0,1]
	global_store_dwordx4 v[120:121], v[112:115], off nt
	global_store_dwordx4 v[120:121], v[116:119], off offset:16 nt
	v_cvt_pk_bf16_f32 v120, v112, v113
	v_mul_f32_e32 v113, v113, v113
	v_fmac_f32_e32 v113, v112, v112
	v_mul_f32_e32 v112, v115, v115
	v_fmac_f32_e32 v112, v114, v114
	v_add_f32_e32 v112, v113, v112
	v_mul_f32_e32 v113, v117, v117
	v_fmac_f32_e32 v113, v116, v116
	v_add_f32_e32 v112, v113, v112
	v_mul_f32_e32 v113, v119, v119
	v_cvt_pk_bf16_f32 v121, v114, v115
	v_fmac_f32_e32 v113, v118, v118
	v_and_b32_e32 v114, 64, v199
	v_add_f32_e32 v112, v113, v112
	v_xor_b32_e32 v113, 16, v199
	v_add_u32_e32 v114, 64, v114
	v_cmp_lt_i32_e32 vcc, v113, v114
	v_add_f32_e32 v112, v155, v112
	v_cvt_pk_bf16_f32 v122, v116, v117
	v_cndmask_b32_e32 v113, v199, v113, vcc
	v_lshlrev_b32_e32 v115, 2, v113
	ds_bpermute_b32 v113, v115, v112
	v_cvt_pk_bf16_f32 v123, v118, v119
	v_lshl_add_u64 v[124:125], v[148:149], 1, s[62:63]
	global_store_dwordx4 v[124:125], v[120:123], off
	s_waitcnt lgkmcnt(0)
	v_add_f32_e32 v112, v112, v113
	v_xor_b32_e32 v113, 32, v199
	v_cmp_lt_i32_e32 vcc, v113, v114
	s_nop 1
	v_cndmask_b32_e32 v113, v199, v113, vcc
	v_lshlrev_b32_e32 v120, 2, v113
	ds_bpermute_b32 v113, v120, v112
	s_and_saveexec_b64 s[14:15], s[48:49]
	s_cbranch_execz .LBB0_1280
	s_waitcnt lgkmcnt(0)
	v_add_f32_e32 v112, v112, v113
	v_mul_f32_e32 v112, 0x4f800000, v112
	v_rndne_f32_e32 v112, v112
	v_mul_f32_e32 v113, 0x2f800000, v112
	v_floor_f32_e32 v113, v113
	v_fmac_f32_e32 v112, 0xcf800000, v113
	v_cvt_u32_f32_e32 v112, v112
	v_cvt_u32_f32_e32 v113, v113
	v_lshl_add_u64 v[224:225], v[146:147], 3, s[58:59]
	v_mov_b32_e32 v226, v112
	v_mov_b32_e32 v227, v113
; DI void ss_add(ssacc_t* p, float v) { atomicAdd(p, (ssacc_t)__float2ull_rn(v * 4294967296.f)); }
; DI float ss_get(const ssacc_t* p) { const ssacc_t v = *p; return (float)(unsigned)(v >> 32) + (float)(unsigned)(v & 0xffffffffull) * 2.3283064365386963e-10f; }
; DI float quad_sum(float s) { s += __shfl_xor(s, 16); s += __shfl_xor(s, 32); return s; }
; DI float sq8(const f32x4& a, const f32x4& b) { return (a[0] * a[0] + a[1] * a[1]) + (a[2] * a[2] + a[3] * a[3]) + (b[0] * b[0] + b[1] * b[1]) + (b[2] * b[2] + b[3] * b[3]); }
; DI u32x4 pack8(const f32x4& a, const f32x4& b) { u32x4 w; w.x = cvtpk(a[0], a[1]); w.y = cvtpk(a[2], a[3]); w.z = cvtpk(b[0], b[1]); w.w = cvtpk(b[2], b[3]); return w; }
;     DI void operator()(const Acc& acc, const Unit& u, int wr, int wc, int fr, int fq) const {
;     ...
;             for (int m = 0; m < 4; ++m) {
;                 asm volatile("" ::: "memory");
;                 const int row = u.pm * 256 + ai * 128 + wr * 64 + m * 16 + fr;
;                 const float rs = rsqrtf(ss_get(ss_dil + row) * (1.f / 512.f) + EPS_);
;                 float sq = 0.f;
; #pragma unroll
;                 for (int bj = 0; bj < 2; ++bj) {
;                     const size_t off = (size_t)row * 2048 + u.pn * 256 + bj * 128 + wc * 32 + 8 * fq;
;                     const f32x4 v0 = *(const f32x4*)(xin + off) + acc[ai][bj][m][0] * rs, v1 = *(const f32x4*)(xin + off + 4) + acc[ai][bj][m][1] * rs;
;                     *(f32x4*)(X + off) = v0; *(f32x4*)(X + off + 4) = v1; *(u32x4*)(XB + off) = pack8(v0, v1); sq += sq8(v0, v1);
;                 }
;                 sq = quad_sum(sq); if (fq == 0) ss_add(ssx1 + row, sq);
.LBB0_1280:
	s_or_b64 exec, exec, s[14:15]
	v_or_b32_e32 v112, 16, v146
	s_waitcnt lgkmcnt(0)
	v_ashrrev_i32_e32 v113, 31, v112
	s_waitcnt vmcnt(9)
	v_mov_b32_e32 v116, v210
	v_mov_b32_e32 v117, v211
	v_mov_b32_e32 v128, v117
	v_lshlrev_b64 v[118:119], s16, v[128:129]
	v_min_u32_e32 v114, 1, v118
	v_or_b32_e32 v114, v119, v114
	v_cvt_f32_u32_e32 v114, v114
	v_cvt_f32_u32_e32 v116, v116
	v_ldexp_f32 v114, v114, s17
	v_fmac_f32_e32 v114, 0x2f800000, v116
	v_fmamk_f32 v114, v114, 0x3b000000, v195
	v_cmp_gt_f32_e32 vcc, s27, v114
	v_mul_f32_e32 v116, 0x4b800000, v114
	s_nop 0
	v_cndmask_b32_e32 v114, v114, v116, vcc
	v_rsq_f32_e32 v114, v114
	s_nop 0
	v_mul_f32_e32 v116, 0x45800000, v114
	v_cndmask_b32_e32 v114, v114, v116, vcc
	v_lshlrev_b64 v[116:117], 11, v[112:113]
	v_lshl_add_u64 v[116:117], v[116:117], 0, v[130:131]
	v_lshlrev_b64 v[126:127], 2, v[116:117]
	v_lshl_add_u64 v[118:119], s[8:9], 0, v[126:127]
	global_load_dwordx4 v[122:125], v[118:119], off offset:16
	global_load_dwordx4 v[148:151], v[118:119], off
	global_load_dwordx4 v[166:169], v[118:119], off offset:528
	global_load_dwordx4 v[170:173], v[118:119], off offset:512
	s_waitcnt vmcnt(3)
	v_pk_fma_f32 v[108:109], v[108:109], v[114:115], v[122:123] op_sel_hi:[1,0,1]
	s_waitcnt vmcnt(2)
	v_pk_fma_f32 v[106:107], v[106:107], v[114:115], v[150:151] op_sel_hi:[1,0,1]
	v_pk_fma_f32 v[104:105], v[104:105], v[114:115], v[148:149] op_sel_hi:[1,0,1]
	v_lshl_add_u64 v[122:123], s[60:61], 0, v[126:127]
	v_pk_fma_f32 v[110:111], v[110:111], v[114:115], v[124:125] op_sel_hi:[1,0,1]
	global_store_dwordx4 v[122:123], v[104:107], off nt
	global_store_dwordx4 v[122:123], v[108:111], off offset:16 nt
	v_cvt_pk_bf16_f32 v122, v104, v105
	v_mul_f32_e32 v105, v105, v105
	v_fmac_f32_e32 v105, v104, v104
	v_mul_f32_e32 v104, v107, v107
	v_fmac_f32_e32 v104, v106, v106
	v_add_f32_e32 v104, v105, v104
	v_mul_f32_e32 v105, v109, v109
	v_fmac_f32_e32 v105, v108, v108
	v_cvt_pk_bf16_f32 v123, v106, v107
	v_cvt_pk_bf16_f32 v124, v108, v109
	v_cvt_pk_bf16_f32 v125, v110, v111
	v_lshl_add_u64 v[126:127], v[116:117], 1, s[62:63]
	v_add_f32_e32 v104, v105, v104
	v_mul_f32_e32 v105, v111, v111
	global_store_dwordx4 v[126:127], v[122:125], off
	v_fmac_f32_e32 v105, v110, v110
	v_add_f32_e32 v121, v105, v104
	v_or_b32_e32 v116, 0x80, v116
	s_waitcnt vmcnt(3)
	v_mov_b32_e32 v104, v166
	v_mov_b32_e32 v105, v167
	v_mov_b32_e32 v106, v168
	v_mov_b32_e32 v107, v169
	v_mov_b32_e32 v108, v170
	v_mov_b32_e32 v109, v171
	v_mov_b32_e32 v110, v172
	v_mov_b32_e32 v111, v173
	v_pk_fma_f32 v[100:101], v[100:101], v[114:115], v[104:105] op_sel_hi:[1,0,1]
	v_pk_fma_f32 v[98:99], v[98:99], v[114:115], v[110:111] op_sel_hi:[1,0,1]
	v_pk_fma_f32 v[96:97], v[96:97], v[114:115], v[108:109] op_sel_hi:[1,0,1]
	v_lshl_add_u64 v[104:105], v[116:117], 2, s[60:61]
	v_pk_fma_f32 v[102:103], v[102:103], v[114:115], v[106:107] op_sel_hi:[1,0,1]
	global_store_dwordx4 v[104:105], v[96:99], off nt
	global_store_dwordx4 v[104:105], v[100:103], off offset:16 nt
	v_cvt_pk_bf16_f32 v104, v96, v97
	v_mul_f32_e32 v97, v97, v97
	v_fmac_f32_e32 v97, v96, v96
	v_mul_f32_e32 v96, v99, v99
	v_fmac_f32_e32 v96, v98, v98
	v_add_f32_e32 v96, v97, v96
	v_mul_f32_e32 v97, v101, v101
	v_fmac_f32_e32 v97, v100, v100
	v_add_f32_e32 v96, v97, v96
	v_mul_f32_e32 v97, v103, v103
	v_fmac_f32_e32 v97, v102, v102
	v_add_f32_e32 v96, v97, v96
	v_add_f32_e32 v96, v121, v96
	ds_bpermute_b32 v97, v115, v96
	v_cvt_pk_bf16_f32 v105, v98, v99
	v_cvt_pk_bf16_f32 v106, v100, v101
	v_cvt_pk_bf16_f32 v107, v102, v103
	v_lshl_add_u64 v[108:109], v[116:117], 1, s[62:63]
	s_waitcnt lgkmcnt(0)
	v_add_f32_e32 v96, v96, v97
	ds_bpermute_b32 v97, v120, v96
	global_store_dwordx4 v[108:109], v[104:107], off
	s_and_saveexec_b64 s[14:15], s[48:49]
	s_cbranch_execz .LBB0_1282
	s_waitcnt lgkmcnt(0)
	v_add_f32_e32 v96, v96, v97
	v_mul_f32_e32 v96, 0x4f800000, v96
	v_rndne_f32_e32 v96, v96
	v_mul_f32_e32 v97, 0x2f800000, v96
	v_floor_f32_e32 v97, v97
	v_fmac_f32_e32 v96, 0xcf800000, v97
	v_cvt_u32_f32_e32 v96, v96
	v_cvt_u32_f32_e32 v97, v97
	v_mov_b32_e32 v228, v96
	v_mov_b32_e32 v229, v97
.LBB0_1282:
	s_or_b64 exec, exec, s[14:15]
	v_or_b32_e32 v96, 32, v146
	s_waitcnt lgkmcnt(0)
	v_ashrrev_i32_e32 v97, 31, v96
	s_waitcnt vmcnt(11)
	v_mov_b32_e32 v98, v212
	v_mov_b32_e32 v99, v213
	v_mov_b32_e32 v128, v99
	v_lshlrev_b64 v[100:101], s16, v[128:129]
	v_min_u32_e32 v99, 1, v100
	v_or_b32_e32 v99, v101, v99
	v_lshlrev_b64 v[100:101], 11, v[96:97]
	v_lshl_add_u64 v[100:101], v[100:101], 0, v[130:131]
	v_lshlrev_b64 v[112:113], 2, v[100:101]
	v_lshl_add_u64 v[102:103], s[8:9], 0, v[112:113]
	global_load_dwordx4 v[104:107], v[102:103], off offset:16
	global_load_dwordx4 v[108:111], v[102:103], off
	global_load_dwordx4 v[166:169], v[102:103], off offset:528
	global_load_dwordx4 v[170:173], v[102:103], off offset:512
	v_cvt_f32_u32_e32 v99, v99
	v_cvt_f32_u32_e32 v98, v98
	v_ldexp_f32 v99, v99, s17
	v_fmac_f32_e32 v99, 0x2f800000, v98
	v_fmamk_f32 v98, v99, 0x3b000000, v195
	v_cmp_gt_f32_e32 vcc, s27, v98
	v_mul_f32_e32 v99, 0x4b800000, v98
	s_nop 0
	v_cndmask_b32_e32 v98, v98, v99, vcc
	v_rsq_f32_e32 v98, v98
	s_nop 0
	v_mul_f32_e32 v99, 0x45800000, v98
	v_cndmask_b32_e32 v98, v98, v99, vcc
	s_waitcnt vmcnt(3)
	v_pk_fma_f32 v[92:93], v[92:93], v[98:99], v[104:105] op_sel_hi:[1,0,1]
	s_waitcnt vmcnt(2)
; DI void ss_add(ssacc_t* p, float v) { atomicAdd(p, (ssacc_t)__float2ull_rn(v * 4294967296.f)); }
; DI float ss_get(const ssacc_t* p) { const ssacc_t v = *p; return (float)(unsigned)(v >> 32) + (float)(unsigned)(v & 0xffffffffull) * 2.3283064365386963e-10f; }
; DI float quad_sum(float s) { s += __shfl_xor(s, 16); s += __shfl_xor(s, 32); return s; }
; DI float sq8(const f32x4& a, const f32x4& b) { return (a[0] * a[0] + a[1] * a[1]) + (a[2] * a[2] + a[3] * a[3]) + (b[0] * b[0] + b[1] * b[1]) + (b[2] * b[2] + b[3] * b[3]); }
; DI u32x4 pack8(const f32x4& a, const f32x4& b) { u32x4 w; w.x = cvtpk(a[0], a[1]); w.y = cvtpk(a[2], a[3]); w.z = cvtpk(b[0], b[1]); w.w = cvtpk(b[2], b[3]); return w; }
;     DI void operator()(const Acc& acc, const Unit& u, int wr, int wc, int fr, int fq) const {
;     ...
;             for (int m = 0; m < 4; ++m) {
;                 asm volatile("" ::: "memory");
;                 const int row = u.pm * 256 + ai * 128 + wr * 64 + m * 16 + fr;
;                 const float rs = rsqrtf(ss_get(ss_dil + row) * (1.f / 512.f) + EPS_);
;                 float sq = 0.f;
; #pragma unroll
;                 for (int bj = 0; bj < 2; ++bj) {
;                     const size_t off = (size_t)row * 2048 + u.pn * 256 + bj * 128 + wc * 32 + 8 * fq;
;                     const f32x4 v0 = *(const f32x4*)(xin + off) + acc[ai][bj][m][0] * rs, v1 = *(const f32x4*)(xin + off + 4) + acc[ai][bj][m][1] * rs;
;                     *(f32x4*)(X + off) = v0; *(f32x4*)(X + off + 4) = v1; *(u32x4*)(XB + off) = pack8(v0, v1); sq += sq8(v0, v1);
;                 }
;                 sq = quad_sum(sq); if (fq == 0) ss_add(ssx1 + row, sq);
	v_pk_fma_f32 v[90:91], v[90:91], v[98:99], v[110:111] op_sel_hi:[1,0,1]
	v_pk_fma_f32 v[88:89], v[88:89], v[98:99], v[108:109] op_sel_hi:[1,0,1]
	v_lshl_add_u64 v[104:105], s[60:61], 0, v[112:113]
	v_pk_fma_f32 v[94:95], v[94:95], v[98:99], v[106:107] op_sel_hi:[1,0,1]
	global_store_dwordx4 v[104:105], v[88:91], off nt
	global_store_dwordx4 v[104:105], v[92:95], off offset:16 nt
	v_cvt_pk_bf16_f32 v104, v88, v89
	v_mul_f32_e32 v89, v89, v89
	v_fmac_f32_e32 v89, v88, v88
	v_mul_f32_e32 v88, v91, v91
	v_fmac_f32_e32 v88, v90, v90
	v_add_f32_e32 v88, v89, v88
	v_mul_f32_e32 v89, v93, v93
	v_fmac_f32_e32 v89, v92, v92
	v_cvt_pk_bf16_f32 v105, v90, v91
	v_cvt_pk_bf16_f32 v106, v92, v93
	v_cvt_pk_bf16_f32 v107, v94, v95
	v_lshl_add_u64 v[108:109], v[100:101], 1, s[62:63]
	v_add_f32_e32 v88, v89, v88
	v_mul_f32_e32 v89, v95, v95
	global_store_dwordx4 v[108:109], v[104:107], off
	v_fmac_f32_e32 v89, v94, v94
	v_add_f32_e32 v99, v89, v88
	v_or_b32_e32 v100, 0x80, v100
	s_waitcnt vmcnt(3)
	v_mov_b32_e32 v88, v166
	v_mov_b32_e32 v89, v167
	v_mov_b32_e32 v90, v168
	v_mov_b32_e32 v91, v169
	v_mov_b32_e32 v92, v170
	v_mov_b32_e32 v93, v171
	v_mov_b32_e32 v94, v172
	v_mov_b32_e32 v95, v173
	v_pk_fma_f32 v[84:85], v[84:85], v[98:99], v[88:89] op_sel_hi:[1,0,1]
	v_pk_fma_f32 v[82:83], v[82:83], v[98:99], v[94:95] op_sel_hi:[1,0,1]
	v_pk_fma_f32 v[80:81], v[80:81], v[98:99], v[92:93] op_sel_hi:[1,0,1]
	v_lshl_add_u64 v[88:89], v[100:101], 2, s[60:61]
	v_pk_fma_f32 v[86:87], v[86:87], v[98:99], v[90:91] op_sel_hi:[1,0,1]
	global_store_dwordx4 v[88:89], v[80:83], off nt
	global_store_dwordx4 v[88:89], v[84:87], off offset:16 nt
	v_cvt_pk_bf16_f32 v88, v80, v81
	v_mul_f32_e32 v81, v81, v81
	v_fmac_f32_e32 v81, v80, v80
	v_mul_f32_e32 v80, v83, v83
	v_fmac_f32_e32 v80, v82, v82
	v_add_f32_e32 v80, v81, v80
	v_mul_f32_e32 v81, v85, v85
	v_fmac_f32_e32 v81, v84, v84
	v_add_f32_e32 v80, v81, v80
	v_mul_f32_e32 v81, v87, v87
	v_fmac_f32_e32 v81, v86, v86
	v_add_f32_e32 v80, v81, v80
	v_add_f32_e32 v80, v99, v80
	ds_bpermute_b32 v81, v115, v80
	v_cvt_pk_bf16_f32 v89, v82, v83
	v_cvt_pk_bf16_f32 v90, v84, v85
	v_cvt_pk_bf16_f32 v91, v86, v87
	v_lshl_add_u64 v[92:93], v[100:101], 1, s[62:63]
	s_waitcnt lgkmcnt(0)
	v_add_f32_e32 v80, v80, v81
	ds_bpermute_b32 v81, v120, v80
	global_store_dwordx4 v[92:93], v[88:91], off
	s_and_saveexec_b64 s[14:15], s[48:49]
	s_cbranch_execz .LBB0_1284
	s_waitcnt lgkmcnt(0)
	v_add_f32_e32 v80, v80, v81
	v_mul_f32_e32 v80, 0x4f800000, v80
	v_rndne_f32_e32 v80, v80
	v_mul_f32_e32 v81, 0x2f800000, v80
	v_floor_f32_e32 v81, v81
	v_fmac_f32_e32 v80, 0xcf800000, v81
	v_cvt_u32_f32_e32 v80, v80
	v_cvt_u32_f32_e32 v81, v81
	v_mov_b32_e32 v230, v80
	v_mov_b32_e32 v231, v81
.LBB0_1284:
	s_or_b64 exec, exec, s[14:15]
	v_or_b32_e32 v80, 48, v146
	s_waitcnt lgkmcnt(0)
	v_ashrrev_i32_e32 v81, 31, v80
	s_waitcnt vmcnt(13)
	v_mov_b32_e32 v82, v214
	v_mov_b32_e32 v83, v215
	v_mov_b32_e32 v128, v83
	v_lshlrev_b64 v[84:85], s16, v[128:129]
	v_min_u32_e32 v83, 1, v84
	v_or_b32_e32 v83, v85, v83
	v_lshlrev_b64 v[84:85], 11, v[80:81]
	v_lshl_add_u64 v[84:85], v[84:85], 0, v[130:131]
	v_lshlrev_b64 v[96:97], 2, v[84:85]
	v_lshl_add_u64 v[86:87], s[8:9], 0, v[96:97]
	global_load_dwordx4 v[88:91], v[86:87], off offset:16
	global_load_dwordx4 v[92:95], v[86:87], off
	global_load_dwordx4 v[166:169], v[86:87], off offset:528
	global_load_dwordx4 v[170:173], v[86:87], off offset:512
	v_cvt_f32_u32_e32 v83, v83
	v_cvt_f32_u32_e32 v82, v82
	v_ldexp_f32 v83, v83, s17
	v_fmac_f32_e32 v83, 0x2f800000, v82
	v_fmamk_f32 v82, v83, 0x3b000000, v195
	v_cmp_gt_f32_e32 vcc, s27, v82
	v_mul_f32_e32 v83, 0x4b800000, v82
	s_nop 0
	v_cndmask_b32_e32 v82, v82, v83, vcc
	v_rsq_f32_e32 v82, v82
	s_nop 0
	v_mul_f32_e32 v83, 0x45800000, v82
	v_cndmask_b32_e32 v82, v82, v83, vcc
	s_waitcnt vmcnt(3)
	v_pk_fma_f32 v[76:77], v[76:77], v[82:83], v[88:89] op_sel_hi:[1,0,1]
	s_waitcnt vmcnt(2)
	v_pk_fma_f32 v[74:75], v[74:75], v[82:83], v[94:95] op_sel_hi:[1,0,1]
	v_pk_fma_f32 v[72:73], v[72:73], v[82:83], v[92:93] op_sel_hi:[1,0,1]
	v_lshl_add_u64 v[88:89], s[60:61], 0, v[96:97]
	v_pk_fma_f32 v[78:79], v[78:79], v[82:83], v[90:91] op_sel_hi:[1,0,1]
	global_store_dwordx4 v[88:89], v[72:75], off nt
	global_store_dwordx4 v[88:89], v[76:79], off offset:16 nt
	v_cvt_pk_bf16_f32 v88, v72, v73
	v_mul_f32_e32 v73, v73, v73
	v_fmac_f32_e32 v73, v72, v72
	v_mul_f32_e32 v72, v75, v75
	v_fmac_f32_e32 v72, v74, v74
	v_add_f32_e32 v72, v73, v72
	v_mul_f32_e32 v73, v77, v77
	v_fmac_f32_e32 v73, v76, v76
	v_cvt_pk_bf16_f32 v89, v74, v75
	v_cvt_pk_bf16_f32 v90, v76, v77
	v_cvt_pk_bf16_f32 v91, v78, v79
	v_lshl_add_u64 v[92:93], v[84:85], 1, s[62:63]
	v_add_f32_e32 v72, v73, v72
	v_mul_f32_e32 v73, v79, v79
	global_store_dwordx4 v[92:93], v[88:91], off
	v_fmac_f32_e32 v73, v78, v78
	v_add_f32_e32 v83, v73, v72
	v_or_b32_e32 v84, 0x80, v84
	s_waitcnt vmcnt(3)
	v_mov_b32_e32 v72, v166
	v_mov_b32_e32 v73, v167
	v_mov_b32_e32 v74, v168
	v_mov_b32_e32 v75, v169
	v_mov_b32_e32 v76, v170
	v_mov_b32_e32 v77, v171
	v_mov_b32_e32 v78, v172
	v_mov_b32_e32 v79, v173
	v_pk_fma_f32 v[68:69], v[68:69], v[82:83], v[72:73] op_sel_hi:[1,0,1]
	v_pk_fma_f32 v[66:67], v[66:67], v[82:83], v[78:79] op_sel_hi:[1,0,1]
	v_pk_fma_f32 v[64:65], v[64:65], v[82:83], v[76:77] op_sel_hi:[1,0,1]
	v_lshl_add_u64 v[72:73], v[84:85], 2, s[60:61]
	v_pk_fma_f32 v[70:71], v[70:71], v[82:83], v[74:75] op_sel_hi:[1,0,1]
	global_store_dwordx4 v[72:73], v[64:67], off nt
	global_store_dwordx4 v[72:73], v[68:71], off offset:16 nt
	v_cvt_pk_bf16_f32 v72, v64, v65
	v_mul_f32_e32 v65, v65, v65
	v_fmac_f32_e32 v65, v64, v64
	v_mul_f32_e32 v64, v67, v67
	v_fmac_f32_e32 v64, v66, v66
	v_add_f32_e32 v64, v65, v64
	v_mul_f32_e32 v65, v69, v69
	v_fmac_f32_e32 v65, v68, v68
	v_add_f32_e32 v64, v65, v64
	v_mul_f32_e32 v65, v71, v71
	v_fmac_f32_e32 v65, v70, v70
	v_add_f32_e32 v64, v65, v64
	v_add_f32_e32 v64, v83, v64
	ds_bpermute_b32 v65, v115, v64
	v_cvt_pk_bf16_f32 v73, v66, v67
	v_cvt_pk_bf16_f32 v74, v68, v69
	v_cvt_pk_bf16_f32 v75, v70, v71
	v_lshl_add_u64 v[76:77], v[84:85], 1, s[62:63]
	s_waitcnt lgkmcnt(0)
	v_add_f32_e32 v64, v64, v65
	ds_bpermute_b32 v65, v120, v64
	global_store_dwordx4 v[76:77], v[72:75], off
	s_and_saveexec_b64 s[14:15], s[48:49]
	s_cbranch_execz .LBB0_1286
	s_waitcnt lgkmcnt(0)
	v_add_f32_e32 v64, v64, v65
	v_mul_f32_e32 v64, 0x4f800000, v64
	v_rndne_f32_e32 v64, v64
	v_mul_f32_e32 v65, 0x2f800000, v64
	v_floor_f32_e32 v65, v65
	v_fmac_f32_e32 v64, 0xcf800000, v65
	v_cvt_u32_f32_e32 v64, v64
	v_cvt_u32_f32_e32 v65, v65
	v_mov_b32_e32 v232, v64
	v_mov_b32_e32 v233, v65
; DI void ss_add(ssacc_t* p, float v) { atomicAdd(p, (ssacc_t)__float2ull_rn(v * 4294967296.f)); }
; DI float ss_get(const ssacc_t* p) { const ssacc_t v = *p; return (float)(unsigned)(v >> 32) + (float)(unsigned)(v & 0xffffffffull) * 2.3283064365386963e-10f; }
; DI float quad_sum(float s) { s += __shfl_xor(s, 16); s += __shfl_xor(s, 32); return s; }
; DI float sq8(const f32x4& a, const f32x4& b) { return (a[0] * a[0] + a[1] * a[1]) + (a[2] * a[2] + a[3] * a[3]) + (b[0] * b[0] + b[1] * b[1]) + (b[2] * b[2] + b[3] * b[3]); }
; DI u32x4 pack8(const f32x4& a, const f32x4& b) { u32x4 w; w.x = cvtpk(a[0], a[1]); w.y = cvtpk(a[2], a[3]); w.z = cvtpk(b[0], b[1]); w.w = cvtpk(b[2], b[3]); return w; }
;     DI void operator()(const Acc& acc, const Unit& u, int wr, int wc, int fr, int fq) const {
;     ...
;             for (int m = 0; m < 4; ++m) {
;                 asm volatile("" ::: "memory");
;                 const int row = u.pm * 256 + ai * 128 + wr * 64 + m * 16 + fr;
;                 const float rs = rsqrtf(ss_get(ss_dil + row) * (1.f / 512.f) + EPS_);
;                 float sq = 0.f;
; #pragma unroll
;                 for (int bj = 0; bj < 2; ++bj) {
;                     const size_t off = (size_t)row * 2048 + u.pn * 256 + bj * 128 + wc * 32 + 8 * fq;
;                     const f32x4 v0 = *(const f32x4*)(xin + off) + acc[ai][bj][m][0] * rs, v1 = *(const f32x4*)(xin + off + 4) + acc[ai][bj][m][1] * rs;
;                     *(f32x4*)(X + off) = v0; *(f32x4*)(X + off + 4) = v1; *(u32x4*)(XB + off) = pack8(v0, v1); sq += sq8(v0, v1);
;                 }
;                 sq = quad_sum(sq); if (fq == 0) ss_add(ssx1 + row, sq);
.LBB0_1286:
	s_or_b64 exec, exec, s[14:15]
	v_add_u32_e32 v64, 0x80, v146
	s_waitcnt lgkmcnt(0)
	v_ashrrev_i32_e32 v65, 31, v64
	s_waitcnt vmcnt(15)
	v_mov_b32_e32 v66, v216
	v_mov_b32_e32 v67, v217
	v_mov_b32_e32 v128, v67
	v_lshlrev_b64 v[68:69], s16, v[128:129]
	v_min_u32_e32 v67, 1, v68
	v_or_b32_e32 v67, v69, v67
	v_lshlrev_b64 v[68:69], 11, v[64:65]
	v_lshl_add_u64 v[68:69], v[68:69], 0, v[130:131]
	v_lshlrev_b64 v[80:81], 2, v[68:69]
	v_lshl_add_u64 v[70:71], s[8:9], 0, v[80:81]
	global_load_dwordx4 v[72:75], v[70:71], off offset:16
	global_load_dwordx4 v[76:79], v[70:71], off
	global_load_dwordx4 v[166:169], v[70:71], off offset:528
	global_load_dwordx4 v[170:173], v[70:71], off offset:512
	v_cvt_f32_u32_e32 v67, v67
	v_cvt_f32_u32_e32 v66, v66
	v_ldexp_f32 v67, v67, s17
	v_fmac_f32_e32 v67, 0x2f800000, v66
	v_fmamk_f32 v66, v67, 0x3b000000, v195
	v_cmp_gt_f32_e32 vcc, s27, v66
	v_mul_f32_e32 v67, 0x4b800000, v66
	s_nop 0
	v_cndmask_b32_e32 v66, v66, v67, vcc
	v_rsq_f32_e32 v66, v66
	s_nop 0
	v_mul_f32_e32 v67, 0x45800000, v66
	v_cndmask_b32_e32 v66, v66, v67, vcc
	s_waitcnt vmcnt(3)
	v_pk_fma_f32 v[60:61], v[60:61], v[66:67], v[72:73] op_sel_hi:[1,0,1]
	s_waitcnt vmcnt(2)
	v_pk_fma_f32 v[58:59], v[58:59], v[66:67], v[78:79] op_sel_hi:[1,0,1]
	v_pk_fma_f32 v[56:57], v[56:57], v[66:67], v[76:77] op_sel_hi:[1,0,1]
	v_lshl_add_u64 v[72:73], s[60:61], 0, v[80:81]
	v_pk_fma_f32 v[62:63], v[62:63], v[66:67], v[74:75] op_sel_hi:[1,0,1]
	global_store_dwordx4 v[72:73], v[56:59], off nt
	global_store_dwordx4 v[72:73], v[60:63], off offset:16 nt
	v_cvt_pk_bf16_f32 v72, v56, v57
	v_mul_f32_e32 v57, v57, v57
	v_fmac_f32_e32 v57, v56, v56
	v_mul_f32_e32 v56, v59, v59
	v_fmac_f32_e32 v56, v58, v58
	v_add_f32_e32 v56, v57, v56
	v_mul_f32_e32 v57, v61, v61
	v_fmac_f32_e32 v57, v60, v60
	v_cvt_pk_bf16_f32 v73, v58, v59
	v_cvt_pk_bf16_f32 v74, v60, v61
	v_cvt_pk_bf16_f32 v75, v62, v63
	v_lshl_add_u64 v[76:77], v[68:69], 1, s[62:63]
	v_add_f32_e32 v56, v57, v56
	v_mul_f32_e32 v57, v63, v63
	global_store_dwordx4 v[76:77], v[72:75], off
	v_fmac_f32_e32 v57, v62, v62
	v_add_f32_e32 v67, v57, v56
	v_or_b32_e32 v68, 0x80, v68
	s_waitcnt vmcnt(3)
	v_mov_b32_e32 v56, v166
	v_mov_b32_e32 v57, v167
	v_mov_b32_e32 v58, v168
	v_mov_b32_e32 v59, v169
	v_mov_b32_e32 v60, v170
	v_mov_b32_e32 v61, v171
	v_mov_b32_e32 v62, v172
	v_mov_b32_e32 v63, v173
	v_pk_fma_f32 v[52:53], v[52:53], v[66:67], v[56:57] op_sel_hi:[1,0,1]
	v_pk_fma_f32 v[50:51], v[50:51], v[66:67], v[62:63] op_sel_hi:[1,0,1]
	v_pk_fma_f32 v[48:49], v[48:49], v[66:67], v[60:61] op_sel_hi:[1,0,1]
	v_lshl_add_u64 v[56:57], v[68:69], 2, s[60:61]
	v_pk_fma_f32 v[54:55], v[54:55], v[66:67], v[58:59] op_sel_hi:[1,0,1]
	global_store_dwordx4 v[56:57], v[48:51], off nt
	global_store_dwordx4 v[56:57], v[52:55], off offset:16 nt
	v_cvt_pk_bf16_f32 v56, v48, v49
	v_mul_f32_e32 v49, v49, v49
	v_fmac_f32_e32 v49, v48, v48
	v_mul_f32_e32 v48, v51, v51
	v_fmac_f32_e32 v48, v50, v50
	v_add_f32_e32 v48, v49, v48
	v_mul_f32_e32 v49, v53, v53
	v_fmac_f32_e32 v49, v52, v52
	v_add_f32_e32 v48, v49, v48
	v_mul_f32_e32 v49, v55, v55
	v_fmac_f32_e32 v49, v54, v54
	v_add_f32_e32 v48, v49, v48
	v_add_f32_e32 v48, v67, v48
	ds_bpermute_b32 v49, v115, v48
	v_cvt_pk_bf16_f32 v57, v50, v51
	v_cvt_pk_bf16_f32 v58, v52, v53
	v_cvt_pk_bf16_f32 v59, v54, v55
	v_lshl_add_u64 v[60:61], v[68:69], 1, s[62:63]
	s_waitcnt lgkmcnt(0)
	v_add_f32_e32 v48, v48, v49
	ds_bpermute_b32 v49, v120, v48
	global_store_dwordx4 v[60:61], v[56:59], off
	s_and_saveexec_b64 s[14:15], s[48:49]
	s_cbranch_execz .LBB0_1288
	s_waitcnt lgkmcnt(0)
	v_add_f32_e32 v48, v48, v49
	v_mul_f32_e32 v48, 0x4f800000, v48
	v_rndne_f32_e32 v48, v48
	v_mul_f32_e32 v49, 0x2f800000, v48
	v_floor_f32_e32 v49, v49
	v_fmac_f32_e32 v48, 0xcf800000, v49
	v_cvt_u32_f32_e32 v48, v48
	v_cvt_u32_f32_e32 v49, v49
	v_mov_b32_e32 v234, v48
	v_mov_b32_e32 v235, v49
.LBB0_1288:
	s_or_b64 exec, exec, s[14:15]
	v_add_u32_e32 v48, 0x90, v146
	s_waitcnt lgkmcnt(0)
	v_ashrrev_i32_e32 v49, 31, v48
	s_waitcnt vmcnt(17)
	v_mov_b32_e32 v50, v218
	v_mov_b32_e32 v51, v219
	v_mov_b32_e32 v128, v51
	v_lshlrev_b64 v[52:53], s16, v[128:129]
	v_min_u32_e32 v51, 1, v52
	v_or_b32_e32 v51, v53, v51
	v_lshlrev_b64 v[52:53], 11, v[48:49]
	v_lshl_add_u64 v[52:53], v[52:53], 0, v[130:131]
	v_lshlrev_b64 v[64:65], 2, v[52:53]
	v_lshl_add_u64 v[54:55], s[8:9], 0, v[64:65]
	global_load_dwordx4 v[56:59], v[54:55], off offset:16
	global_load_dwordx4 v[60:63], v[54:55], off
	global_load_dwordx4 v[166:169], v[54:55], off offset:528
	global_load_dwordx4 v[170:173], v[54:55], off offset:512
	v_cvt_f32_u32_e32 v51, v51
	v_cvt_f32_u32_e32 v50, v50
	v_ldexp_f32 v51, v51, s17
	v_fmac_f32_e32 v51, 0x2f800000, v50
	v_fmamk_f32 v50, v51, 0x3b000000, v195
	v_cmp_gt_f32_e32 vcc, s27, v50
	v_mul_f32_e32 v51, 0x4b800000, v50
	s_nop 0
	v_cndmask_b32_e32 v50, v50, v51, vcc
	v_rsq_f32_e32 v50, v50
	s_nop 0
	v_mul_f32_e32 v51, 0x45800000, v50
	v_cndmask_b32_e32 v50, v50, v51, vcc
	s_waitcnt vmcnt(3)
	v_pk_fma_f32 v[44:45], v[44:45], v[50:51], v[56:57] op_sel_hi:[1,0,1]
	s_waitcnt vmcnt(2)
	v_pk_fma_f32 v[42:43], v[42:43], v[50:51], v[62:63] op_sel_hi:[1,0,1]
	v_pk_fma_f32 v[40:41], v[40:41], v[50:51], v[60:61] op_sel_hi:[1,0,1]
	v_lshl_add_u64 v[56:57], s[60:61], 0, v[64:65]
	v_pk_fma_f32 v[46:47], v[46:47], v[50:51], v[58:59] op_sel_hi:[1,0,1]
	global_store_dwordx4 v[56:57], v[40:43], off nt
	global_store_dwordx4 v[56:57], v[44:47], off offset:16 nt
	v_cvt_pk_bf16_f32 v56, v40, v41
	v_mul_f32_e32 v41, v41, v41
	v_fmac_f32_e32 v41, v40, v40
	v_mul_f32_e32 v40, v43, v43
	v_fmac_f32_e32 v40, v42, v42
	v_add_f32_e32 v40, v41, v40
	v_mul_f32_e32 v41, v45, v45
	v_fmac_f32_e32 v41, v44, v44
	v_cvt_pk_bf16_f32 v57, v42, v43
	v_cvt_pk_bf16_f32 v58, v44, v45
	v_cvt_pk_bf16_f32 v59, v46, v47
	v_lshl_add_u64 v[60:61], v[52:53], 1, s[62:63]
	v_add_f32_e32 v40, v41, v40
	v_mul_f32_e32 v41, v47, v47
	global_store_dwordx4 v[60:61], v[56:59], off
	v_fmac_f32_e32 v41, v46, v46
	v_add_f32_e32 v51, v41, v40
	v_or_b32_e32 v52, 0x80, v52
	s_waitcnt vmcnt(3)
; DI void ss_add(ssacc_t* p, float v) { atomicAdd(p, (ssacc_t)__float2ull_rn(v * 4294967296.f)); }
; DI float ss_get(const ssacc_t* p) { const ssacc_t v = *p; return (float)(unsigned)(v >> 32) + (float)(unsigned)(v & 0xffffffffull) * 2.3283064365386963e-10f; }
; DI float quad_sum(float s) { s += __shfl_xor(s, 16); s += __shfl_xor(s, 32); return s; }
; DI float sq8(const f32x4& a, const f32x4& b) { return (a[0] * a[0] + a[1] * a[1]) + (a[2] * a[2] + a[3] * a[3]) + (b[0] * b[0] + b[1] * b[1]) + (b[2] * b[2] + b[3] * b[3]); }
; DI u32x4 pack8(const f32x4& a, const f32x4& b) { u32x4 w; w.x = cvtpk(a[0], a[1]); w.y = cvtpk(a[2], a[3]); w.z = cvtpk(b[0], b[1]); w.w = cvtpk(b[2], b[3]); return w; }
;     DI void operator()(const Acc& acc, const Unit& u, int wr, int wc, int fr, int fq) const {
;     ...
;             for (int m = 0; m < 4; ++m) {
;                 asm volatile("" ::: "memory");
;                 const int row = u.pm * 256 + ai * 128 + wr * 64 + m * 16 + fr;
;                 const float rs = rsqrtf(ss_get(ss_dil + row) * (1.f / 512.f) + EPS_);
;                 float sq = 0.f;
; #pragma unroll
;                 for (int bj = 0; bj < 2; ++bj) {
;                     const size_t off = (size_t)row * 2048 + u.pn * 256 + bj * 128 + wc * 32 + 8 * fq;
;                     const f32x4 v0 = *(const f32x4*)(xin + off) + acc[ai][bj][m][0] * rs, v1 = *(const f32x4*)(xin + off + 4) + acc[ai][bj][m][1] * rs;
;                     *(f32x4*)(X + off) = v0; *(f32x4*)(X + off + 4) = v1; *(u32x4*)(XB + off) = pack8(v0, v1); sq += sq8(v0, v1);
;                 }
;                 sq = quad_sum(sq); if (fq == 0) ss_add(ssx1 + row, sq);
	v_mov_b32_e32 v40, v166
	v_mov_b32_e32 v41, v167
	v_mov_b32_e32 v42, v168
	v_mov_b32_e32 v43, v169
	v_mov_b32_e32 v44, v170
	v_mov_b32_e32 v45, v171
	v_mov_b32_e32 v46, v172
	v_mov_b32_e32 v47, v173
	v_pk_fma_f32 v[36:37], v[36:37], v[50:51], v[40:41] op_sel_hi:[1,0,1]
	v_pk_fma_f32 v[34:35], v[34:35], v[50:51], v[46:47] op_sel_hi:[1,0,1]
	v_pk_fma_f32 v[32:33], v[32:33], v[50:51], v[44:45] op_sel_hi:[1,0,1]
	v_lshl_add_u64 v[40:41], v[52:53], 2, s[60:61]
	v_pk_fma_f32 v[38:39], v[38:39], v[50:51], v[42:43] op_sel_hi:[1,0,1]
	global_store_dwordx4 v[40:41], v[32:35], off nt
	global_store_dwordx4 v[40:41], v[36:39], off offset:16 nt
	v_cvt_pk_bf16_f32 v40, v32, v33
	v_mul_f32_e32 v33, v33, v33
	v_fmac_f32_e32 v33, v32, v32
	v_mul_f32_e32 v32, v35, v35
	v_fmac_f32_e32 v32, v34, v34
	v_add_f32_e32 v32, v33, v32
	v_mul_f32_e32 v33, v37, v37
	v_fmac_f32_e32 v33, v36, v36
	v_add_f32_e32 v32, v33, v32
	v_mul_f32_e32 v33, v39, v39
	v_fmac_f32_e32 v33, v38, v38
	v_add_f32_e32 v32, v33, v32
	v_add_f32_e32 v32, v51, v32
	ds_bpermute_b32 v33, v115, v32
	v_cvt_pk_bf16_f32 v41, v34, v35
	v_cvt_pk_bf16_f32 v42, v36, v37
	v_cvt_pk_bf16_f32 v43, v38, v39
	v_lshl_add_u64 v[44:45], v[52:53], 1, s[62:63]
	s_waitcnt lgkmcnt(0)
	v_add_f32_e32 v32, v32, v33
	ds_bpermute_b32 v33, v120, v32
	global_store_dwordx4 v[44:45], v[40:43], off
	s_and_saveexec_b64 s[14:15], s[48:49]
	s_cbranch_execz .LBB0_1290
	s_waitcnt lgkmcnt(0)
	v_add_f32_e32 v32, v32, v33
	v_mul_f32_e32 v32, 0x4f800000, v32
	v_rndne_f32_e32 v32, v32
	v_mul_f32_e32 v33, 0x2f800000, v32
	v_floor_f32_e32 v33, v33
	v_fmac_f32_e32 v32, 0xcf800000, v33
	v_cvt_u32_f32_e32 v32, v32
	v_cvt_u32_f32_e32 v33, v33
	v_mov_b32_e32 v236, v32
	v_mov_b32_e32 v237, v33
.LBB0_1290:
	s_or_b64 exec, exec, s[14:15]
	v_add_u32_e32 v32, 0xa0, v146
	s_waitcnt lgkmcnt(0)
	v_ashrrev_i32_e32 v33, 31, v32
	s_waitcnt vmcnt(19)
	v_mov_b32_e32 v34, v220
	v_mov_b32_e32 v35, v221
	v_mov_b32_e32 v128, v35
	v_lshlrev_b64 v[36:37], s16, v[128:129]
	v_min_u32_e32 v35, 1, v36
	v_or_b32_e32 v35, v37, v35
	v_lshlrev_b64 v[36:37], 11, v[32:33]
	v_lshl_add_u64 v[36:37], v[36:37], 0, v[130:131]
	v_lshlrev_b64 v[48:49], 2, v[36:37]
	v_lshl_add_u64 v[38:39], s[8:9], 0, v[48:49]
	global_load_dwordx4 v[40:43], v[38:39], off offset:16
	global_load_dwordx4 v[44:47], v[38:39], off
	global_load_dwordx4 v[166:169], v[38:39], off offset:528
	global_load_dwordx4 v[170:173], v[38:39], off offset:512
	v_cvt_f32_u32_e32 v35, v35
	v_cvt_f32_u32_e32 v34, v34
	v_ldexp_f32 v35, v35, s17
	v_fmac_f32_e32 v35, 0x2f800000, v34
	v_fmamk_f32 v34, v35, 0x3b000000, v195
	v_cmp_gt_f32_e32 vcc, s27, v34
	v_mul_f32_e32 v35, 0x4b800000, v34
	s_nop 0
	v_cndmask_b32_e32 v34, v34, v35, vcc
	v_rsq_f32_e32 v34, v34
	s_nop 0
	v_mul_f32_e32 v35, 0x45800000, v34
	v_cndmask_b32_e32 v34, v34, v35, vcc
	s_waitcnt vmcnt(3)
	v_pk_fma_f32 v[28:29], v[28:29], v[34:35], v[40:41] op_sel_hi:[1,0,1]
	s_waitcnt vmcnt(2)
	v_pk_fma_f32 v[26:27], v[26:27], v[34:35], v[46:47] op_sel_hi:[1,0,1]
	v_pk_fma_f32 v[24:25], v[24:25], v[34:35], v[44:45] op_sel_hi:[1,0,1]
	v_lshl_add_u64 v[40:41], s[60:61], 0, v[48:49]
	v_pk_fma_f32 v[30:31], v[30:31], v[34:35], v[42:43] op_sel_hi:[1,0,1]
	global_store_dwordx4 v[40:41], v[24:27], off nt
	global_store_dwordx4 v[40:41], v[28:31], off offset:16 nt
	v_cvt_pk_bf16_f32 v40, v24, v25
	v_mul_f32_e32 v25, v25, v25
	v_fmac_f32_e32 v25, v24, v24
	v_mul_f32_e32 v24, v27, v27
	v_fmac_f32_e32 v24, v26, v26
	v_add_f32_e32 v24, v25, v24
	v_mul_f32_e32 v25, v29, v29
	v_fmac_f32_e32 v25, v28, v28
	v_cvt_pk_bf16_f32 v41, v26, v27
	v_cvt_pk_bf16_f32 v42, v28, v29
	v_cvt_pk_bf16_f32 v43, v30, v31
	v_lshl_add_u64 v[44:45], v[36:37], 1, s[62:63]
	v_add_f32_e32 v24, v25, v24
	v_mul_f32_e32 v25, v31, v31
	global_store_dwordx4 v[44:45], v[40:43], off
	v_fmac_f32_e32 v25, v30, v30
	v_add_f32_e32 v35, v25, v24
	v_or_b32_e32 v36, 0x80, v36
	s_waitcnt vmcnt(3)
	v_mov_b32_e32 v24, v166
	v_mov_b32_e32 v25, v167
	v_mov_b32_e32 v26, v168
	v_mov_b32_e32 v27, v169
	v_mov_b32_e32 v28, v170
	v_mov_b32_e32 v29, v171
	v_mov_b32_e32 v30, v172
	v_mov_b32_e32 v31, v173
	v_pk_fma_f32 v[20:21], v[20:21], v[34:35], v[24:25] op_sel_hi:[1,0,1]
	v_pk_fma_f32 v[18:19], v[18:19], v[34:35], v[30:31] op_sel_hi:[1,0,1]
	v_pk_fma_f32 v[16:17], v[16:17], v[34:35], v[28:29] op_sel_hi:[1,0,1]
	v_lshl_add_u64 v[24:25], v[36:37], 2, s[60:61]
	v_pk_fma_f32 v[22:23], v[22:23], v[34:35], v[26:27] op_sel_hi:[1,0,1]
	global_store_dwordx4 v[24:25], v[16:19], off nt
	global_store_dwordx4 v[24:25], v[20:23], off offset:16 nt
	v_cvt_pk_bf16_f32 v24, v16, v17
	v_mul_f32_e32 v17, v17, v17
	v_fmac_f32_e32 v17, v16, v16
	v_mul_f32_e32 v16, v19, v19
	v_fmac_f32_e32 v16, v18, v18
	v_add_f32_e32 v16, v17, v16
	v_mul_f32_e32 v17, v21, v21
	v_fmac_f32_e32 v17, v20, v20
	v_add_f32_e32 v16, v17, v16
	v_mul_f32_e32 v17, v23, v23
	v_fmac_f32_e32 v17, v22, v22
	v_add_f32_e32 v16, v17, v16
	v_add_f32_e32 v16, v35, v16
	ds_bpermute_b32 v17, v115, v16
	v_cvt_pk_bf16_f32 v25, v18, v19
	v_cvt_pk_bf16_f32 v26, v20, v21
	v_cvt_pk_bf16_f32 v27, v22, v23
	v_lshl_add_u64 v[28:29], v[36:37], 1, s[62:63]
	s_waitcnt lgkmcnt(0)
	v_add_f32_e32 v16, v16, v17
	ds_bpermute_b32 v17, v120, v16
	global_store_dwordx4 v[28:29], v[24:27], off
	s_and_saveexec_b64 s[14:15], s[48:49]
	s_cbranch_execz .LBB0_1292
	s_waitcnt lgkmcnt(0)
	v_add_f32_e32 v16, v16, v17
	v_mul_f32_e32 v16, 0x4f800000, v16
	v_rndne_f32_e32 v16, v16
	v_mul_f32_e32 v17, 0x2f800000, v16
	v_floor_f32_e32 v17, v17
	v_fmac_f32_e32 v16, 0xcf800000, v17
	v_cvt_u32_f32_e32 v16, v16
	v_cvt_u32_f32_e32 v17, v17
	v_mov_b32_e32 v238, v16
	v_mov_b32_e32 v239, v17
; DI void ss_add(ssacc_t* p, float v) { atomicAdd(p, (ssacc_t)__float2ull_rn(v * 4294967296.f)); }
; DI float ss_get(const ssacc_t* p) { const ssacc_t v = *p; return (float)(unsigned)(v >> 32) + (float)(unsigned)(v & 0xffffffffull) * 2.3283064365386963e-10f; }
; DI float quad_sum(float s) { s += __shfl_xor(s, 16); s += __shfl_xor(s, 32); return s; }
; DI float sq8(const f32x4& a, const f32x4& b) { return (a[0] * a[0] + a[1] * a[1]) + (a[2] * a[2] + a[3] * a[3]) + (b[0] * b[0] + b[1] * b[1]) + (b[2] * b[2] + b[3] * b[3]); }
; DI u32x4 pack8(const f32x4& a, const f32x4& b) { u32x4 w; w.x = cvtpk(a[0], a[1]); w.y = cvtpk(a[2], a[3]); w.z = cvtpk(b[0], b[1]); w.w = cvtpk(b[2], b[3]); return w; }
;     DI void operator()(const Acc& acc, const Unit& u, int wr, int wc, int fr, int fq) const {
;     ...
;             for (int m = 0; m < 4; ++m) {
;                 asm volatile("" ::: "memory");
;                 const int row = u.pm * 256 + ai * 128 + wr * 64 + m * 16 + fr;
;                 const float rs = rsqrtf(ss_get(ss_dil + row) * (1.f / 512.f) + EPS_);
;                 float sq = 0.f;
; #pragma unroll
;                 for (int bj = 0; bj < 2; ++bj) {
;                     const size_t off = (size_t)row * 2048 + u.pn * 256 + bj * 128 + wc * 32 + 8 * fq;
;                     const f32x4 v0 = *(const f32x4*)(xin + off) + acc[ai][bj][m][0] * rs, v1 = *(const f32x4*)(xin + off + 4) + acc[ai][bj][m][1] * rs;
;                     *(f32x4*)(X + off) = v0; *(f32x4*)(X + off + 4) = v1; *(u32x4*)(XB + off) = pack8(v0, v1); sq += sq8(v0, v1);
;                 }
;                 sq = quad_sum(sq); if (fq == 0) ss_add(ssx1 + row, sq);
.LBB0_1292:
	s_or_b64 exec, exec, s[14:15]
	v_add_u32_e32 v16, 0xb0, v146
	s_waitcnt lgkmcnt(0)
	v_ashrrev_i32_e32 v17, 31, v16
	s_waitcnt vmcnt(21)
	v_mov_b32_e32 v18, v222
	v_mov_b32_e32 v19, v223
	v_mov_b32_e32 v128, v19
	v_lshlrev_b64 v[20:21], s16, v[128:129]
	v_min_u32_e32 v19, 1, v20
	v_or_b32_e32 v19, v21, v19
	v_lshlrev_b64 v[20:21], 11, v[16:17]
	v_lshl_add_u64 v[20:21], v[20:21], 0, v[130:131]
	v_lshlrev_b64 v[32:33], 2, v[20:21]
	v_lshl_add_u64 v[22:23], s[8:9], 0, v[32:33]
	global_load_dwordx4 v[24:27], v[22:23], off offset:16
	global_load_dwordx4 v[28:31], v[22:23], off
	global_load_dwordx4 v[166:169], v[22:23], off offset:528
	global_load_dwordx4 v[170:173], v[22:23], off offset:512
	v_cvt_f32_u32_e32 v19, v19
	v_cvt_f32_u32_e32 v18, v18
	v_ldexp_f32 v19, v19, s17
	v_fmac_f32_e32 v19, 0x2f800000, v18
	v_fmamk_f32 v18, v19, 0x3b000000, v195
	v_cmp_gt_f32_e32 vcc, s27, v18
	v_mul_f32_e32 v19, 0x4b800000, v18
	s_nop 0
	v_cndmask_b32_e32 v18, v18, v19, vcc
	v_rsq_f32_e32 v18, v18
	s_nop 0
	v_mul_f32_e32 v19, 0x45800000, v18
	v_cndmask_b32_e32 v18, v18, v19, vcc
	s_waitcnt vmcnt(3)
	v_pk_fma_f32 v[12:13], v[12:13], v[18:19], v[24:25] op_sel_hi:[1,0,1]
	s_waitcnt vmcnt(2)
	v_pk_fma_f32 v[10:11], v[10:11], v[18:19], v[30:31] op_sel_hi:[1,0,1]
	v_pk_fma_f32 v[8:9], v[8:9], v[18:19], v[28:29] op_sel_hi:[1,0,1]
	v_lshl_add_u64 v[24:25], s[60:61], 0, v[32:33]
	v_pk_fma_f32 v[14:15], v[14:15], v[18:19], v[26:27] op_sel_hi:[1,0,1]
	global_store_dwordx4 v[24:25], v[8:11], off nt
	global_store_dwordx4 v[24:25], v[12:15], off offset:16 nt
	v_cvt_pk_bf16_f32 v24, v8, v9
	v_mul_f32_e32 v9, v9, v9
	v_fmac_f32_e32 v9, v8, v8
	v_mul_f32_e32 v8, v11, v11
	v_fmac_f32_e32 v8, v10, v10
	v_add_f32_e32 v8, v9, v8
	v_mul_f32_e32 v9, v13, v13
	v_fmac_f32_e32 v9, v12, v12
	v_cvt_pk_bf16_f32 v25, v10, v11
	v_cvt_pk_bf16_f32 v26, v12, v13
	v_cvt_pk_bf16_f32 v27, v14, v15
	v_lshl_add_u64 v[28:29], v[20:21], 1, s[62:63]
	v_add_f32_e32 v8, v9, v8
	v_mul_f32_e32 v9, v15, v15
	global_store_dwordx4 v[28:29], v[24:27], off
	v_fmac_f32_e32 v9, v14, v14
	v_add_f32_e32 v19, v9, v8
	v_or_b32_e32 v20, 0x80, v20
	s_waitcnt vmcnt(3)
	v_mov_b32_e32 v8, v166
	v_mov_b32_e32 v9, v167
	v_mov_b32_e32 v10, v168
	v_mov_b32_e32 v11, v169
	v_mov_b32_e32 v12, v170
	v_mov_b32_e32 v13, v171
	v_mov_b32_e32 v14, v172
	v_mov_b32_e32 v15, v173
	v_pk_fma_f32 v[4:5], v[4:5], v[18:19], v[8:9] op_sel_hi:[1,0,1]
	v_pk_fma_f32 v[2:3], v[2:3], v[18:19], v[14:15] op_sel_hi:[1,0,1]
	v_pk_fma_f32 v[0:1], v[0:1], v[18:19], v[12:13] op_sel_hi:[1,0,1]
	v_lshl_add_u64 v[8:9], v[20:21], 2, s[60:61]
	v_pk_fma_f32 v[6:7], v[6:7], v[18:19], v[10:11] op_sel_hi:[1,0,1]
	global_store_dwordx4 v[8:9], v[0:3], off nt
	global_store_dwordx4 v[8:9], v[4:7], off offset:16 nt
	v_cvt_pk_bf16_f32 v8, v0, v1
	v_mul_f32_e32 v1, v1, v1
	v_fmac_f32_e32 v1, v0, v0
	v_mul_f32_e32 v0, v3, v3
	v_fmac_f32_e32 v0, v2, v2
	v_add_f32_e32 v0, v1, v0
	v_mul_f32_e32 v1, v5, v5
	v_fmac_f32_e32 v1, v4, v4
	v_add_f32_e32 v0, v1, v0
	v_mul_f32_e32 v1, v7, v7
	v_fmac_f32_e32 v1, v6, v6
	v_add_f32_e32 v0, v1, v0
	v_add_f32_e32 v0, v19, v0
	ds_bpermute_b32 v1, v115, v0
	v_cvt_pk_bf16_f32 v9, v2, v3
	v_cvt_pk_bf16_f32 v10, v4, v5
	v_cvt_pk_bf16_f32 v11, v6, v7
	v_lshl_add_u64 v[12:13], v[20:21], 1, s[62:63]
	s_waitcnt lgkmcnt(0)
	v_add_f32_e32 v0, v0, v1
	ds_bpermute_b32 v1, v120, v0
	global_store_dwordx4 v[12:13], v[8:11], off
	s_and_saveexec_b64 s[14:15], s[48:49]
	s_cbranch_execz .LBB0_1294
	s_waitcnt lgkmcnt(0)
	v_add_f32_e32 v0, v0, v1
	v_mul_f32_e32 v0, 0x4f800000, v0
	v_rndne_f32_e32 v0, v0
	v_mul_f32_e32 v1, 0x2f800000, v0
	v_floor_f32_e32 v1, v1
	v_fmac_f32_e32 v0, 0xcf800000, v1
	v_cvt_u32_f32_e32 v0, v0
	v_cvt_u32_f32_e32 v1, v1
	v_lshl_add_u64 v[2:3], v[16:17], 3, s[58:59]
	global_atomic_add_x2 v[224:225], v[226:227], off
	global_atomic_add_x2 v[224:225], v[228:229], off offset:128
	global_atomic_add_x2 v[224:225], v[230:231], off offset:256
	global_atomic_add_x2 v[224:225], v[232:233], off offset:384
	global_atomic_add_x2 v[224:225], v[234:235], off offset:1024
	global_atomic_add_x2 v[224:225], v[236:237], off offset:1152
	global_atomic_add_x2 v[224:225], v[238:239], off offset:1280
	global_atomic_add_x2 v[2:3], v[0:1], off

; DI void ss_add(ssacc_t* p, float v) { atomicAdd(p, (ssacc_t)__float2ull_rn(v * 4294967296.f)); }
; DI float quad_sum(float s) { s += __shfl_xor(s, 16); s += __shfl_xor(s, 32); return s; }
; DI float sq8(const f32x4& a, const f32x4& b) { return (a[0] * a[0] + a[1] * a[1]) + (a[2] * a[2] + a[3] * a[3]) + (b[0] * b[0] + b[1] * b[1]) + (b[2] * b[2] + b[3] * b[3]); }
; DI u32x4 pack8(const f32x4& a, const f32x4& b) { u32x4 w; w.x = cvtpk(a[0], a[1]); w.y = cvtpk(a[2], a[3]); w.z = cvtpk(b[0], b[1]); w.w = cvtpk(b[2], b[3]); return w; }
;     DI void operator()(const Acc& acc, const Unit& u, int wr, int wc, int fr, int fq) const {
;     ...
;                 asm volatile("" ::: "memory");
;                 const int row = u.pm * 256 + ai * 128 + wr * 64 + m * 16 + fr;
;                 float sq = 0.f;
; #pragma unroll
;                 for (int bj = 0; bj < 2; ++bj) {
;                     const size_t off = (size_t)row * 2048 + u.pn * 256 + bj * 128 + wc * 32 + 8 * fq;
;                     const f32x4 v0 = *(const f32x4*)(X + off) + acc[ai][bj][m][0], v1 = *(const f32x4*)(X + off + 4) + acc[ai][bj][m][1];
;                     *(f32x4*)(X + off) = v0; *(f32x4*)(X + off + 4) = v1; *(u32x4*)(XB + off) = pack8(v0, v1); sq += sq8(v0, v1);
;                 }
;                 sq = quad_sum(sq); if (fq == 0) ss_add(ssx + row, sq);
.LBB0_1567:
	v_lshl_add_u32 v144, s66, 8, v137
	s_lshl_b32 s4, s65, 8
	s_ashr_i32 s14, s4, 31
	v_ashrrev_i32_e32 v145, 31, v144
	v_mov_b32_e32 v143, s14
	v_or_b32_e32 v142, s4, v136
	v_lshlrev_b64 v[148:149], 11, v[144:145]
	v_lshl_add_u64 v[156:157], v[148:149], 0, v[142:143]
	v_lshl_add_u64 v[158:159], v[156:157], 2, s[44:45]
	v_mov_b32_e32 v190, v158
	v_mov_b32_e32 v191, v159
	global_load_dwordx4 v[160:163], v[158:159], off offset:16
	global_load_dwordx4 v[164:167], v[158:159], off
	s_mov_b64 s[100:101], 0x200
	v_lshl_add_u64 v[192:193], v[190:191], 0, s[100:101]
	global_load_dwordx4 v[168:171], v[192:193], off offset:16
	global_load_dwordx4 v[172:175], v[192:193], off
	s_mov_b64 s[100:101], 0x20000
	v_lshl_add_u64 v[192:193], v[190:191], 0, s[100:101]
	global_load_dwordx4 v[176:179], v[192:193], off offset:16
	global_load_dwordx4 v[180:183], v[192:193], off
	s_mov_b64 s[100:101], 0x20200
	v_lshl_add_u64 v[192:193], v[190:191], 0, s[100:101]
	global_load_dwordx4 v[208:211], v[192:193], off offset:16
	global_load_dwordx4 v[212:215], v[192:193], off
	s_mov_b64 s[100:101], 0x40000
	v_lshl_add_u64 v[192:193], v[190:191], 0, s[100:101]
	global_load_dwordx4 v[216:219], v[192:193], off offset:16
	global_load_dwordx4 v[220:223], v[192:193], off
	s_mov_b64 s[100:101], 0x40200
	v_lshl_add_u64 v[192:193], v[190:191], 0, s[100:101]
	global_load_dwordx4 v[224:227], v[192:193], off offset:16
	global_load_dwordx4 v[228:231], v[192:193], off
	s_waitcnt vmcnt(10)
	v_mov_b32_e32 v148, v160
	v_mov_b32_e32 v149, v161
	v_mov_b32_e32 v150, v162
	v_mov_b32_e32 v151, v163
	v_mov_b32_e32 v152, v164
	v_mov_b32_e32 v153, v165
	v_mov_b32_e32 v154, v166
	v_mov_b32_e32 v155, v167
	s_mov_b64 s[100:101], 0x60000
	v_lshl_add_u64 v[192:193], v[190:191], 0, s[100:101]
	global_load_dwordx4 v[160:163], v[192:193], off offset:16
	global_load_dwordx4 v[164:167], v[192:193], off
	v_pk_add_f32 v[126:127], v[126:127], v[150:151]
	v_pk_add_f32 v[122:123], v[122:123], v[154:155]
	v_pk_add_f32 v[120:121], v[120:121], v[152:153]
	v_pk_add_f32 v[124:125], v[124:125], v[148:149]
	global_store_dwordx4 v[158:159], v[120:123], off nt
	global_store_dwordx4 v[158:159], v[124:127], off offset:16 nt
	v_cvt_pk_bf16_f32 v148, v120, v121
	v_mul_f32_e32 v121, v121, v121
	v_fmac_f32_e32 v121, v120, v120
	v_mul_f32_e32 v120, v123, v123
	v_fmac_f32_e32 v120, v122, v122
	v_add_f32_e32 v120, v121, v120
	v_mul_f32_e32 v121, v125, v125
	v_fmac_f32_e32 v121, v124, v124
	v_cvt_pk_bf16_f32 v149, v122, v123
	v_cvt_pk_bf16_f32 v150, v124, v125
	v_cvt_pk_bf16_f32 v151, v126, v127
	v_lshl_add_u64 v[152:153], v[156:157], 1, s[50:51]
	v_add_f32_e32 v120, v120, v121
	v_mul_f32_e32 v121, v127, v127
	v_or_b32_e32 v156, 0x80, v156
	global_store_dwordx4 v[152:153], v[148:151], off
	v_fmac_f32_e32 v121, v126, v126
	s_nop 0
	v_lshl_add_u64 v[148:149], v[156:157], 2, s[44:45]
	v_add_f32_e32 v150, v121, v120
	s_waitcnt vmcnt(13)
	v_mov_b32_e32 v120, v168
	v_mov_b32_e32 v121, v169
	v_mov_b32_e32 v122, v170
	v_mov_b32_e32 v123, v171
	v_mov_b32_e32 v124, v172
	v_mov_b32_e32 v125, v173
	v_mov_b32_e32 v126, v174
	v_mov_b32_e32 v127, v175
	s_mov_b64 s[100:101], 0x60200
	v_lshl_add_u64 v[192:193], v[190:191], 0, s[100:101]
	global_load_dwordx4 v[168:171], v[192:193], off offset:16
	global_load_dwordx4 v[172:175], v[192:193], off
	v_pk_add_f32 v[114:115], v[114:115], v[122:123]
	v_pk_add_f32 v[118:119], v[118:119], v[126:127]
	v_pk_add_f32 v[116:117], v[116:117], v[124:125]
	v_pk_add_f32 v[112:113], v[112:113], v[120:121]
	global_store_dwordx4 v[148:149], v[116:119], off nt
	global_store_dwordx4 v[148:149], v[112:115], off offset:16 nt
	v_cvt_pk_bf16_f32 v120, v116, v117
	v_mul_f32_e32 v117, v117, v117
	v_fmac_f32_e32 v117, v116, v116
	v_mul_f32_e32 v116, v119, v119
	v_cvt_pk_bf16_f32 v122, v112, v113
	v_fmac_f32_e32 v116, v118, v118
	v_mul_f32_e32 v113, v113, v113
	v_add_f32_e32 v116, v117, v116
	v_fmac_f32_e32 v113, v112, v112
	v_add_f32_e32 v112, v116, v113
	v_mul_f32_e32 v113, v115, v115
	v_cvt_pk_bf16_f32 v123, v114, v115
	v_fmac_f32_e32 v113, v114, v114
	v_and_b32_e32 v114, 64, v199
	v_add_f32_e32 v112, v113, v112
	v_xor_b32_e32 v113, 16, v199
	v_add_u32_e32 v115, 64, v114
	v_cmp_lt_i32_e32 vcc, v113, v115
	v_add_f32_e32 v112, v150, v112
	v_cvt_pk_bf16_f32 v121, v118, v119
	v_cndmask_b32_e32 v113, v199, v113, vcc
	v_lshlrev_b32_e32 v116, 2, v113
	ds_bpermute_b32 v113, v116, v112
	v_lshl_add_u64 v[124:125], v[156:157], 1, s[50:51]
	global_store_dwordx4 v[124:125], v[120:123], off
	s_waitcnt lgkmcnt(0)
	v_add_f32_e32 v114, v112, v113
	v_xor_b32_e32 v112, 32, v199
	v_cmp_lt_i32_e32 vcc, v112, v115
	s_nop 1
	v_cndmask_b32_e32 v112, v199, v112, vcc
	v_lshlrev_b32_e32 v117, 2, v112
	ds_bpermute_b32 v115, v117, v114
	v_lshl_add_u64 v[112:113], v[144:145], 3, s[52:53]
	s_and_saveexec_b64 s[14:15], s[46:47]
	s_cbranch_execz .LBB0_1569
	s_waitcnt lgkmcnt(0)
	v_add_f32_e32 v114, v114, v115
	v_mul_f32_e32 v114, 0x4f800000, v114
	v_rndne_f32_e32 v114, v114
	v_mul_f32_e32 v115, 0x2f800000, v114
	v_floor_f32_e32 v115, v115
	v_fmac_f32_e32 v114, 0xcf800000, v115
	v_cvt_u32_f32_e32 v114, v114
	v_cvt_u32_f32_e32 v115, v115
	v_mov_b32_e32 v232, v114
	v_mov_b32_e32 v233, v115
; DI void ss_add(ssacc_t* p, float v) { atomicAdd(p, (ssacc_t)__float2ull_rn(v * 4294967296.f)); }
; DI float quad_sum(float s) { s += __shfl_xor(s, 16); s += __shfl_xor(s, 32); return s; }
; DI float sq8(const f32x4& a, const f32x4& b) { return (a[0] * a[0] + a[1] * a[1]) + (a[2] * a[2] + a[3] * a[3]) + (b[0] * b[0] + b[1] * b[1]) + (b[2] * b[2] + b[3] * b[3]); }
; DI u32x4 pack8(const f32x4& a, const f32x4& b) { u32x4 w; w.x = cvtpk(a[0], a[1]); w.y = cvtpk(a[2], a[3]); w.z = cvtpk(b[0], b[1]); w.w = cvtpk(b[2], b[3]); return w; }
;     DI void operator()(const Acc& acc, const Unit& u, int wr, int wc, int fr, int fq) const {
;     ...
;                 asm volatile("" ::: "memory");
;                 const int row = u.pm * 256 + ai * 128 + wr * 64 + m * 16 + fr;
;                 float sq = 0.f;
; #pragma unroll
;                 for (int bj = 0; bj < 2; ++bj) {
;                     const size_t off = (size_t)row * 2048 + u.pn * 256 + bj * 128 + wc * 32 + 8 * fq;
;                     const f32x4 v0 = *(const f32x4*)(X + off) + acc[ai][bj][m][0], v1 = *(const f32x4*)(X + off + 4) + acc[ai][bj][m][1];
;                     *(f32x4*)(X + off) = v0; *(f32x4*)(X + off + 4) = v1; *(u32x4*)(XB + off) = pack8(v0, v1); sq += sq8(v0, v1);
;                 }
;                 sq = quad_sum(sq); if (fq == 0) ss_add(ssx + row, sq);
.LBB0_1569:
	s_or_b64 exec, exec, s[14:15]
	v_or_b32_e32 v114, 16, v144
	s_waitcnt lgkmcnt(0)
	v_ashrrev_i32_e32 v115, 31, v114
	v_lshlrev_b64 v[114:115], 11, v[114:115]
	v_lshl_add_u64 v[114:115], v[114:115], 0, v[142:143]
	v_lshl_add_u64 v[126:127], v[114:115], 2, s[44:45]
	s_waitcnt vmcnt(16)
	v_mov_b32_e32 v118, v176
	v_mov_b32_e32 v119, v177
	v_mov_b32_e32 v120, v178
	v_mov_b32_e32 v121, v179
	v_mov_b32_e32 v122, v180
	v_mov_b32_e32 v123, v181
	v_mov_b32_e32 v124, v182
	v_mov_b32_e32 v125, v183
	s_mov_b64 s[100:101], 0x100000
	v_lshl_add_u64 v[192:193], v[190:191], 0, s[100:101]
	global_load_dwordx4 v[176:179], v[192:193], off offset:16
	global_load_dwordx4 v[180:183], v[192:193], off
	v_pk_add_f32 v[106:107], v[106:107], v[120:121]
	v_pk_add_f32 v[110:111], v[110:111], v[124:125]
	v_pk_add_f32 v[108:109], v[108:109], v[122:123]
	v_pk_add_f32 v[104:105], v[104:105], v[118:119]
	global_store_dwordx4 v[126:127], v[108:111], off nt
	global_store_dwordx4 v[126:127], v[104:107], off offset:16 nt
	v_cvt_pk_bf16_f32 v118, v108, v109
	v_mul_f32_e32 v109, v109, v109
	v_fmac_f32_e32 v109, v108, v108
	v_mul_f32_e32 v108, v111, v111
	v_cvt_pk_bf16_f32 v120, v104, v105
	v_fmac_f32_e32 v108, v110, v110
	v_mul_f32_e32 v105, v105, v105
	v_add_f32_e32 v108, v109, v108
	v_fmac_f32_e32 v105, v104, v104
	v_cvt_pk_bf16_f32 v119, v110, v111
	v_cvt_pk_bf16_f32 v121, v106, v107
	v_lshl_add_u64 v[122:123], v[114:115], 1, s[50:51]
	v_add_f32_e32 v104, v108, v105
	v_mul_f32_e32 v105, v107, v107
	v_or_b32_e32 v114, 0x80, v114
	global_store_dwordx4 v[122:123], v[118:121], off
	v_fmac_f32_e32 v105, v106, v106
	s_nop 0
	v_lshl_add_u64 v[118:119], v[114:115], 2, s[44:45]
	v_add_f32_e32 v120, v105, v104
	s_waitcnt vmcnt(19)
	v_mov_b32_e32 v104, v208
	v_mov_b32_e32 v105, v209
	v_mov_b32_e32 v106, v210
	v_mov_b32_e32 v107, v211
	v_mov_b32_e32 v108, v212
	v_mov_b32_e32 v109, v213
	v_mov_b32_e32 v110, v214
	v_mov_b32_e32 v111, v215
	s_mov_b64 s[100:101], 0x100200
	v_lshl_add_u64 v[192:193], v[190:191], 0, s[100:101]
	global_load_dwordx4 v[208:211], v[192:193], off offset:16
	global_load_dwordx4 v[212:215], v[192:193], off
	v_pk_add_f32 v[98:99], v[98:99], v[106:107]
	v_pk_add_f32 v[102:103], v[102:103], v[110:111]
	v_pk_add_f32 v[100:101], v[100:101], v[108:109]
	v_pk_add_f32 v[96:97], v[96:97], v[104:105]
	global_store_dwordx4 v[118:119], v[100:103], off nt
	global_store_dwordx4 v[118:119], v[96:99], off offset:16 nt
	v_cvt_pk_bf16_f32 v104, v100, v101
	v_mul_f32_e32 v101, v101, v101
	v_fmac_f32_e32 v101, v100, v100
	v_mul_f32_e32 v100, v103, v103
	v_cvt_pk_bf16_f32 v106, v96, v97
	v_fmac_f32_e32 v100, v102, v102
	v_mul_f32_e32 v97, v97, v97
	v_add_f32_e32 v100, v101, v100
	v_fmac_f32_e32 v97, v96, v96
	v_add_f32_e32 v96, v100, v97
	v_mul_f32_e32 v97, v99, v99
	v_fmac_f32_e32 v97, v98, v98
	v_add_f32_e32 v96, v97, v96
	v_add_f32_e32 v96, v120, v96
	ds_bpermute_b32 v97, v116, v96
	v_cvt_pk_bf16_f32 v105, v102, v103
	v_cvt_pk_bf16_f32 v107, v98, v99
	v_lshl_add_u64 v[108:109], v[114:115], 1, s[50:51]
	global_store_dwordx4 v[108:109], v[104:107], off
	s_waitcnt lgkmcnt(0)
	v_add_f32_e32 v96, v96, v97
	ds_bpermute_b32 v97, v117, v96
	s_and_saveexec_b64 s[14:15], s[46:47]
	s_cbranch_execz .LBB0_1571
	s_waitcnt lgkmcnt(0)
	v_add_f32_e32 v96, v96, v97
	v_mul_f32_e32 v96, 0x4f800000, v96
	v_rndne_f32_e32 v96, v96
	v_mul_f32_e32 v97, 0x2f800000, v96
	v_floor_f32_e32 v97, v97
	v_fmac_f32_e32 v96, 0xcf800000, v97
	v_cvt_u32_f32_e32 v96, v96
	v_cvt_u32_f32_e32 v97, v97
	v_mov_b32_e32 v234, v96
	v_mov_b32_e32 v235, v97
.LBB0_1571:
	s_or_b64 exec, exec, s[14:15]
	v_or_b32_e32 v96, 32, v144
	s_waitcnt lgkmcnt(0)
	v_ashrrev_i32_e32 v97, 31, v96
	v_lshlrev_b64 v[96:97], 11, v[96:97]
	v_lshl_add_u64 v[96:97], v[96:97], 0, v[142:143]
	v_lshl_add_u64 v[106:107], v[96:97], 2, s[44:45]
	s_waitcnt vmcnt(22)
	v_mov_b32_e32 v98, v216
	v_mov_b32_e32 v99, v217
	v_mov_b32_e32 v100, v218
	v_mov_b32_e32 v101, v219
	v_mov_b32_e32 v102, v220
	v_mov_b32_e32 v103, v221
	v_mov_b32_e32 v104, v222
	v_mov_b32_e32 v105, v223
	s_mov_b64 s[100:101], 0x120000
	v_lshl_add_u64 v[192:193], v[190:191], 0, s[100:101]
	global_load_dwordx4 v[216:219], v[192:193], off offset:16
	global_load_dwordx4 v[220:223], v[192:193], off
	v_pk_add_f32 v[90:91], v[90:91], v[100:101]
	v_pk_add_f32 v[94:95], v[94:95], v[104:105]
	v_pk_add_f32 v[92:93], v[92:93], v[102:103]
	v_pk_add_f32 v[88:89], v[88:89], v[98:99]
	global_store_dwordx4 v[106:107], v[92:95], off nt
	global_store_dwordx4 v[106:107], v[88:91], off offset:16 nt
	v_cvt_pk_bf16_f32 v98, v92, v93
	v_mul_f32_e32 v93, v93, v93
	v_fmac_f32_e32 v93, v92, v92
	v_mul_f32_e32 v92, v95, v95
	v_cvt_pk_bf16_f32 v100, v88, v89
	v_fmac_f32_e32 v92, v94, v94
	v_mul_f32_e32 v89, v89, v89
	v_add_f32_e32 v92, v93, v92
	v_fmac_f32_e32 v89, v88, v88
	v_cvt_pk_bf16_f32 v99, v94, v95
	v_cvt_pk_bf16_f32 v101, v90, v91
	v_lshl_add_u64 v[102:103], v[96:97], 1, s[50:51]
	v_add_f32_e32 v88, v92, v89
	v_mul_f32_e32 v89, v91, v91
	v_or_b32_e32 v96, 0x80, v96
	global_store_dwordx4 v[102:103], v[98:101], off
	v_fmac_f32_e32 v89, v90, v90
	s_nop 0
	v_lshl_add_u64 v[98:99], v[96:97], 2, s[44:45]
	v_add_f32_e32 v100, v89, v88
	s_waitcnt vmcnt(25)
	v_mov_b32_e32 v88, v224
	v_mov_b32_e32 v89, v225
	v_mov_b32_e32 v90, v226
	v_mov_b32_e32 v91, v227
	v_mov_b32_e32 v92, v228
	v_mov_b32_e32 v93, v229
	v_mov_b32_e32 v94, v230
	v_mov_b32_e32 v95, v231
	s_mov_b64 s[100:101], 0x120200
	v_lshl_add_u64 v[192:193], v[190:191], 0, s[100:101]
	global_load_dwordx4 v[224:227], v[192:193], off offset:16
	global_load_dwordx4 v[228:231], v[192:193], off
	v_pk_add_f32 v[82:83], v[82:83], v[90:91]
	v_pk_add_f32 v[86:87], v[86:87], v[94:95]
	v_pk_add_f32 v[84:85], v[84:85], v[92:93]
	v_pk_add_f32 v[80:81], v[80:81], v[88:89]
	global_store_dwordx4 v[98:99], v[84:87], off nt
	global_store_dwordx4 v[98:99], v[80:83], off offset:16 nt
	v_cvt_pk_bf16_f32 v88, v84, v85
	v_mul_f32_e32 v85, v85, v85
	v_fmac_f32_e32 v85, v84, v84
	v_mul_f32_e32 v84, v87, v87
	v_cvt_pk_bf16_f32 v90, v80, v81
	v_fmac_f32_e32 v84, v86, v86
	v_mul_f32_e32 v81, v81, v81
	v_add_f32_e32 v84, v85, v84
	v_fmac_f32_e32 v81, v80, v80
	v_add_f32_e32 v80, v84, v81
	v_mul_f32_e32 v81, v83, v83
	v_fmac_f32_e32 v81, v82, v82
	v_add_f32_e32 v80, v81, v80
	v_add_f32_e32 v80, v100, v80
	ds_bpermute_b32 v81, v116, v80
	v_cvt_pk_bf16_f32 v89, v86, v87
	v_cvt_pk_bf16_f32 v91, v82, v83
	v_lshl_add_u64 v[92:93], v[96:97], 1, s[50:51]
	global_store_dwordx4 v[92:93], v[88:91], off
	s_waitcnt lgkmcnt(0)
	v_add_f32_e32 v80, v80, v81
	ds_bpermute_b32 v81, v117, v80
	s_and_saveexec_b64 s[14:15], s[46:47]
	s_cbranch_execz .LBB0_1573
	s_waitcnt lgkmcnt(0)
	v_add_f32_e32 v80, v80, v81
	v_mul_f32_e32 v80, 0x4f800000, v80
	v_rndne_f32_e32 v80, v80
	v_mul_f32_e32 v81, 0x2f800000, v80
	v_floor_f32_e32 v81, v81
	v_fmac_f32_e32 v80, 0xcf800000, v81
	v_cvt_u32_f32_e32 v80, v80
	v_cvt_u32_f32_e32 v81, v81
	v_mov_b32_e32 v236, v80
	v_mov_b32_e32 v237, v81
; DI void ss_add(ssacc_t* p, float v) { atomicAdd(p, (ssacc_t)__float2ull_rn(v * 4294967296.f)); }
; DI float quad_sum(float s) { s += __shfl_xor(s, 16); s += __shfl_xor(s, 32); return s; }
; DI float sq8(const f32x4& a, const f32x4& b) { return (a[0] * a[0] + a[1] * a[1]) + (a[2] * a[2] + a[3] * a[3]) + (b[0] * b[0] + b[1] * b[1]) + (b[2] * b[2] + b[3] * b[3]); }
; DI u32x4 pack8(const f32x4& a, const f32x4& b) { u32x4 w; w.x = cvtpk(a[0], a[1]); w.y = cvtpk(a[2], a[3]); w.z = cvtpk(b[0], b[1]); w.w = cvtpk(b[2], b[3]); return w; }
;     DI void operator()(const Acc& acc, const Unit& u, int wr, int wc, int fr, int fq) const {
;     ...
;                 asm volatile("" ::: "memory");
;                 const int row = u.pm * 256 + ai * 128 + wr * 64 + m * 16 + fr;
;                 float sq = 0.f;
; #pragma unroll
;                 for (int bj = 0; bj < 2; ++bj) {
;                     const size_t off = (size_t)row * 2048 + u.pn * 256 + bj * 128 + wc * 32 + 8 * fq;
;                     const f32x4 v0 = *(const f32x4*)(X + off) + acc[ai][bj][m][0], v1 = *(const f32x4*)(X + off + 4) + acc[ai][bj][m][1];
;                     *(f32x4*)(X + off) = v0; *(f32x4*)(X + off + 4) = v1; *(u32x4*)(XB + off) = pack8(v0, v1); sq += sq8(v0, v1);
;                 }
;                 sq = quad_sum(sq); if (fq == 0) ss_add(ssx + row, sq);
.LBB0_1573:
	s_or_b64 exec, exec, s[14:15]
	v_or_b32_e32 v80, 48, v144
	s_waitcnt lgkmcnt(0)
	v_ashrrev_i32_e32 v81, 31, v80
	v_lshlrev_b64 v[80:81], 11, v[80:81]
	v_lshl_add_u64 v[80:81], v[80:81], 0, v[142:143]
	v_lshl_add_u64 v[90:91], v[80:81], 2, s[44:45]
	s_waitcnt vmcnt(28)
	v_mov_b32_e32 v82, v160
	v_mov_b32_e32 v83, v161
	v_mov_b32_e32 v84, v162
	v_mov_b32_e32 v85, v163
	v_mov_b32_e32 v86, v164
	v_mov_b32_e32 v87, v165
	v_mov_b32_e32 v88, v166
	v_mov_b32_e32 v89, v167
	s_mov_b64 s[100:101], 0x140000
	v_lshl_add_u64 v[192:193], v[190:191], 0, s[100:101]
	global_load_dwordx4 v[160:163], v[192:193], off offset:16
	global_load_dwordx4 v[164:167], v[192:193], off
	v_pk_add_f32 v[74:75], v[74:75], v[84:85]
	v_pk_add_f32 v[78:79], v[78:79], v[88:89]
	v_pk_add_f32 v[76:77], v[76:77], v[86:87]
	v_pk_add_f32 v[72:73], v[72:73], v[82:83]
	global_store_dwordx4 v[90:91], v[76:79], off nt
	global_store_dwordx4 v[90:91], v[72:75], off offset:16 nt
	v_cvt_pk_bf16_f32 v82, v76, v77
	v_mul_f32_e32 v77, v77, v77
	v_fmac_f32_e32 v77, v76, v76
	v_mul_f32_e32 v76, v79, v79
	v_cvt_pk_bf16_f32 v84, v72, v73
	v_fmac_f32_e32 v76, v78, v78
	v_mul_f32_e32 v73, v73, v73
	v_add_f32_e32 v76, v77, v76
	v_fmac_f32_e32 v73, v72, v72
	v_cvt_pk_bf16_f32 v83, v78, v79
	v_cvt_pk_bf16_f32 v85, v74, v75
	v_lshl_add_u64 v[86:87], v[80:81], 1, s[50:51]
	v_add_f32_e32 v72, v76, v73
	v_mul_f32_e32 v73, v75, v75
	v_or_b32_e32 v80, 0x80, v80
	global_store_dwordx4 v[86:87], v[82:85], off
	v_fmac_f32_e32 v73, v74, v74
	s_nop 0
	v_lshl_add_u64 v[82:83], v[80:81], 2, s[44:45]
	v_add_f32_e32 v84, v73, v72
	s_waitcnt vmcnt(28)
	v_mov_b32_e32 v72, v168
	v_mov_b32_e32 v73, v169
	v_mov_b32_e32 v74, v170
	v_mov_b32_e32 v75, v171
	v_mov_b32_e32 v76, v172
	v_mov_b32_e32 v77, v173
	v_mov_b32_e32 v78, v174
	v_mov_b32_e32 v79, v175
	s_mov_b64 s[100:101], 0x140200
	v_lshl_add_u64 v[192:193], v[190:191], 0, s[100:101]
	global_load_dwordx4 v[168:171], v[192:193], off offset:16
	global_load_dwordx4 v[172:175], v[192:193], off
	v_pk_add_f32 v[66:67], v[66:67], v[74:75]
	v_pk_add_f32 v[70:71], v[70:71], v[78:79]
	v_pk_add_f32 v[68:69], v[68:69], v[76:77]
	v_pk_add_f32 v[64:65], v[64:65], v[72:73]
	global_store_dwordx4 v[82:83], v[68:71], off nt
	global_store_dwordx4 v[82:83], v[64:67], off offset:16 nt
	v_cvt_pk_bf16_f32 v72, v68, v69
	v_mul_f32_e32 v69, v69, v69
	v_fmac_f32_e32 v69, v68, v68
	v_mul_f32_e32 v68, v71, v71
	v_cvt_pk_bf16_f32 v74, v64, v65
	v_fmac_f32_e32 v68, v70, v70
	v_mul_f32_e32 v65, v65, v65
	v_add_f32_e32 v68, v69, v68
	v_fmac_f32_e32 v65, v64, v64
	v_add_f32_e32 v64, v68, v65
	v_mul_f32_e32 v65, v67, v67
	v_fmac_f32_e32 v65, v66, v66
	v_add_f32_e32 v64, v65, v64
	v_add_f32_e32 v64, v84, v64
	ds_bpermute_b32 v65, v116, v64
	v_cvt_pk_bf16_f32 v73, v70, v71
	v_cvt_pk_bf16_f32 v75, v66, v67
	v_lshl_add_u64 v[76:77], v[80:81], 1, s[50:51]
	global_store_dwordx4 v[76:77], v[72:75], off
	s_waitcnt lgkmcnt(0)
	v_add_f32_e32 v64, v64, v65
	ds_bpermute_b32 v65, v117, v64
	s_and_saveexec_b64 s[14:15], s[46:47]
	s_cbranch_execz .LBB0_1575
	s_waitcnt lgkmcnt(0)
	v_add_f32_e32 v64, v64, v65
	v_mul_f32_e32 v64, 0x4f800000, v64
	v_rndne_f32_e32 v64, v64
	v_mul_f32_e32 v65, 0x2f800000, v64
	v_floor_f32_e32 v65, v65
	v_fmac_f32_e32 v64, 0xcf800000, v65
	v_cvt_u32_f32_e32 v64, v64
	v_cvt_u32_f32_e32 v65, v65
	v_mov_b32_e32 v238, v64
	v_mov_b32_e32 v239, v65
.LBB0_1575:
	s_or_b64 exec, exec, s[14:15]
	v_add_u32_e32 v64, 0x80, v144
	s_waitcnt lgkmcnt(0)
	v_ashrrev_i32_e32 v65, 31, v64
	v_lshlrev_b64 v[64:65], 11, v[64:65]
	v_lshl_add_u64 v[64:65], v[64:65], 0, v[142:143]
	v_lshl_add_u64 v[74:75], v[64:65], 2, s[44:45]
	s_waitcnt vmcnt(28)
	v_mov_b32_e32 v66, v176
	v_mov_b32_e32 v67, v177
	v_mov_b32_e32 v68, v178
	v_mov_b32_e32 v69, v179
	v_mov_b32_e32 v70, v180
	v_mov_b32_e32 v71, v181
	v_mov_b32_e32 v72, v182
	v_mov_b32_e32 v73, v183
	s_mov_b64 s[100:101], 0x160000
	v_lshl_add_u64 v[192:193], v[190:191], 0, s[100:101]
	global_load_dwordx4 v[176:179], v[192:193], off offset:16
	global_load_dwordx4 v[180:183], v[192:193], off
	v_pk_add_f32 v[58:59], v[58:59], v[68:69]
	v_pk_add_f32 v[62:63], v[62:63], v[72:73]
	v_pk_add_f32 v[60:61], v[60:61], v[70:71]
	v_pk_add_f32 v[56:57], v[56:57], v[66:67]
	global_store_dwordx4 v[74:75], v[60:63], off nt
	global_store_dwordx4 v[74:75], v[56:59], off offset:16 nt
	v_cvt_pk_bf16_f32 v66, v60, v61
	v_mul_f32_e32 v61, v61, v61
	v_fmac_f32_e32 v61, v60, v60
	v_mul_f32_e32 v60, v63, v63
	v_cvt_pk_bf16_f32 v68, v56, v57
	v_fmac_f32_e32 v60, v62, v62
	v_mul_f32_e32 v57, v57, v57
	v_add_f32_e32 v60, v61, v60
	v_fmac_f32_e32 v57, v56, v56
	v_cvt_pk_bf16_f32 v67, v62, v63
	v_cvt_pk_bf16_f32 v69, v58, v59
	v_lshl_add_u64 v[70:71], v[64:65], 1, s[50:51]
	v_add_f32_e32 v56, v60, v57
	v_mul_f32_e32 v57, v59, v59
	v_or_b32_e32 v64, 0x80, v64
	global_store_dwordx4 v[70:71], v[66:69], off
	v_fmac_f32_e32 v57, v58, v58
	s_nop 0
	v_lshl_add_u64 v[66:67], v[64:65], 2, s[44:45]
	v_add_f32_e32 v68, v57, v56
	s_waitcnt vmcnt(28)
	v_mov_b32_e32 v56, v208
	v_mov_b32_e32 v57, v209
	v_mov_b32_e32 v58, v210
	v_mov_b32_e32 v59, v211
	v_mov_b32_e32 v60, v212
	v_mov_b32_e32 v61, v213
	v_mov_b32_e32 v62, v214
	v_mov_b32_e32 v63, v215
	s_mov_b64 s[100:101], 0x160200
	v_lshl_add_u64 v[192:193], v[190:191], 0, s[100:101]
	global_load_dwordx4 v[208:211], v[192:193], off offset:16
	global_load_dwordx4 v[212:215], v[192:193], off
	v_pk_add_f32 v[50:51], v[50:51], v[58:59]
	v_pk_add_f32 v[54:55], v[54:55], v[62:63]
	v_pk_add_f32 v[52:53], v[52:53], v[60:61]
	v_pk_add_f32 v[48:49], v[48:49], v[56:57]
	global_store_dwordx4 v[66:67], v[52:55], off nt
	global_store_dwordx4 v[66:67], v[48:51], off offset:16 nt
	v_cvt_pk_bf16_f32 v56, v52, v53
	v_mul_f32_e32 v53, v53, v53
	v_fmac_f32_e32 v53, v52, v52
	v_mul_f32_e32 v52, v55, v55
	v_cvt_pk_bf16_f32 v58, v48, v49
	v_fmac_f32_e32 v52, v54, v54
	v_mul_f32_e32 v49, v49, v49
	v_add_f32_e32 v52, v53, v52
	v_fmac_f32_e32 v49, v48, v48
	v_add_f32_e32 v48, v52, v49
	v_mul_f32_e32 v49, v51, v51
	v_fmac_f32_e32 v49, v50, v50
	v_add_f32_e32 v48, v49, v48
	v_add_f32_e32 v48, v68, v48
	ds_bpermute_b32 v49, v116, v48
	v_cvt_pk_bf16_f32 v57, v54, v55
	v_cvt_pk_bf16_f32 v59, v50, v51
	v_lshl_add_u64 v[60:61], v[64:65], 1, s[50:51]
	global_store_dwordx4 v[60:61], v[56:59], off
	s_waitcnt lgkmcnt(0)
	v_add_f32_e32 v48, v48, v49
	ds_bpermute_b32 v49, v117, v48
	s_and_saveexec_b64 s[14:15], s[46:47]
	s_cbranch_execz .LBB0_1577
	s_waitcnt lgkmcnt(0)
	v_add_f32_e32 v48, v48, v49
	v_mul_f32_e32 v48, 0x4f800000, v48
	v_rndne_f32_e32 v48, v48
	v_mul_f32_e32 v49, 0x2f800000, v48
	v_floor_f32_e32 v49, v49
	v_fmac_f32_e32 v48, 0xcf800000, v49
	v_cvt_u32_f32_e32 v48, v48
	v_cvt_u32_f32_e32 v49, v49
	v_mov_b32_e32 v240, v48
	v_mov_b32_e32 v241, v49
; DI void ss_add(ssacc_t* p, float v) { atomicAdd(p, (ssacc_t)__float2ull_rn(v * 4294967296.f)); }
; DI float quad_sum(float s) { s += __shfl_xor(s, 16); s += __shfl_xor(s, 32); return s; }
; DI float sq8(const f32x4& a, const f32x4& b) { return (a[0] * a[0] + a[1] * a[1]) + (a[2] * a[2] + a[3] * a[3]) + (b[0] * b[0] + b[1] * b[1]) + (b[2] * b[2] + b[3] * b[3]); }
; DI u32x4 pack8(const f32x4& a, const f32x4& b) { u32x4 w; w.x = cvtpk(a[0], a[1]); w.y = cvtpk(a[2], a[3]); w.z = cvtpk(b[0], b[1]); w.w = cvtpk(b[2], b[3]); return w; }
;     DI void operator()(const Acc& acc, const Unit& u, int wr, int wc, int fr, int fq) const {
;     ...
;                 asm volatile("" ::: "memory");
;                 const int row = u.pm * 256 + ai * 128 + wr * 64 + m * 16 + fr;
;                 float sq = 0.f;
; #pragma unroll
;                 for (int bj = 0; bj < 2; ++bj) {
;                     const size_t off = (size_t)row * 2048 + u.pn * 256 + bj * 128 + wc * 32 + 8 * fq;
;                     const f32x4 v0 = *(const f32x4*)(X + off) + acc[ai][bj][m][0], v1 = *(const f32x4*)(X + off + 4) + acc[ai][bj][m][1];
;                     *(f32x4*)(X + off) = v0; *(f32x4*)(X + off + 4) = v1; *(u32x4*)(XB + off) = pack8(v0, v1); sq += sq8(v0, v1);
;                 }
;                 sq = quad_sum(sq); if (fq == 0) ss_add(ssx + row, sq);
.LBB0_1577:
	s_or_b64 exec, exec, s[14:15]
	v_add_u32_e32 v48, 0x90, v144
	s_waitcnt lgkmcnt(0)
	v_ashrrev_i32_e32 v49, 31, v48
	v_lshlrev_b64 v[48:49], 11, v[48:49]
	v_lshl_add_u64 v[48:49], v[48:49], 0, v[142:143]
	v_lshl_add_u64 v[58:59], v[48:49], 2, s[44:45]
	s_waitcnt vmcnt(28)
	v_mov_b32_e32 v50, v216
	v_mov_b32_e32 v51, v217
	v_mov_b32_e32 v52, v218
	v_mov_b32_e32 v53, v219
	v_mov_b32_e32 v54, v220
	v_mov_b32_e32 v55, v221
	v_mov_b32_e32 v56, v222
	v_mov_b32_e32 v57, v223
	v_pk_add_f32 v[42:43], v[42:43], v[52:53]
	v_pk_add_f32 v[46:47], v[46:47], v[56:57]
	v_pk_add_f32 v[44:45], v[44:45], v[54:55]
	v_pk_add_f32 v[40:41], v[40:41], v[50:51]
	global_store_dwordx4 v[58:59], v[44:47], off nt
	global_store_dwordx4 v[58:59], v[40:43], off offset:16 nt
	v_cvt_pk_bf16_f32 v50, v44, v45
	v_mul_f32_e32 v45, v45, v45
	v_fmac_f32_e32 v45, v44, v44
	v_mul_f32_e32 v44, v47, v47
	v_cvt_pk_bf16_f32 v52, v40, v41
	v_fmac_f32_e32 v44, v46, v46
	v_mul_f32_e32 v41, v41, v41
	v_add_f32_e32 v44, v45, v44
	v_fmac_f32_e32 v41, v40, v40
	v_cvt_pk_bf16_f32 v51, v46, v47
	v_cvt_pk_bf16_f32 v53, v42, v43
	v_lshl_add_u64 v[54:55], v[48:49], 1, s[50:51]
	v_add_f32_e32 v40, v44, v41
	v_mul_f32_e32 v41, v43, v43
	v_or_b32_e32 v48, 0x80, v48
	global_store_dwordx4 v[54:55], v[50:53], off
	v_fmac_f32_e32 v41, v42, v42
	s_nop 0
	v_lshl_add_u64 v[50:51], v[48:49], 2, s[44:45]
	v_add_f32_e32 v52, v41, v40
	s_waitcnt vmcnt(26)
	v_mov_b32_e32 v40, v224
	v_mov_b32_e32 v41, v225
	v_mov_b32_e32 v42, v226
	v_mov_b32_e32 v43, v227
	v_mov_b32_e32 v44, v228
	v_mov_b32_e32 v45, v229
	v_mov_b32_e32 v46, v230
	v_mov_b32_e32 v47, v231
	v_pk_add_f32 v[34:35], v[34:35], v[42:43]
	v_pk_add_f32 v[38:39], v[38:39], v[46:47]
	v_pk_add_f32 v[36:37], v[36:37], v[44:45]
	v_pk_add_f32 v[32:33], v[32:33], v[40:41]
	global_store_dwordx4 v[50:51], v[36:39], off nt
	global_store_dwordx4 v[50:51], v[32:35], off offset:16 nt
	v_cvt_pk_bf16_f32 v40, v36, v37
	v_mul_f32_e32 v37, v37, v37
	v_fmac_f32_e32 v37, v36, v36
	v_mul_f32_e32 v36, v39, v39
	v_cvt_pk_bf16_f32 v42, v32, v33
	v_fmac_f32_e32 v36, v38, v38
	v_mul_f32_e32 v33, v33, v33
	v_add_f32_e32 v36, v37, v36
	v_fmac_f32_e32 v33, v32, v32
	v_add_f32_e32 v32, v36, v33
	v_mul_f32_e32 v33, v35, v35
	v_fmac_f32_e32 v33, v34, v34
	v_add_f32_e32 v32, v33, v32
	v_add_f32_e32 v32, v52, v32
	ds_bpermute_b32 v33, v116, v32
	v_cvt_pk_bf16_f32 v41, v38, v39
	v_cvt_pk_bf16_f32 v43, v34, v35
	v_lshl_add_u64 v[44:45], v[48:49], 1, s[50:51]
	global_store_dwordx4 v[44:45], v[40:43], off
	s_waitcnt lgkmcnt(0)
	v_add_f32_e32 v32, v32, v33
	ds_bpermute_b32 v33, v117, v32
	s_and_saveexec_b64 s[14:15], s[46:47]
	s_cbranch_execz .LBB0_1579
	s_waitcnt lgkmcnt(0)
	v_add_f32_e32 v32, v32, v33
	v_mul_f32_e32 v32, 0x4f800000, v32
	v_rndne_f32_e32 v32, v32
	v_mul_f32_e32 v33, 0x2f800000, v32
	v_floor_f32_e32 v33, v33
	v_fmac_f32_e32 v32, 0xcf800000, v33
	v_cvt_u32_f32_e32 v32, v32
	v_cvt_u32_f32_e32 v33, v33
	v_mov_b32_e32 v242, v32
	v_mov_b32_e32 v243, v33
.LBB0_1579:
	s_or_b64 exec, exec, s[14:15]
	v_add_u32_e32 v32, 0xa0, v144
	s_waitcnt lgkmcnt(0)
	v_ashrrev_i32_e32 v33, 31, v32
	v_lshlrev_b64 v[32:33], 11, v[32:33]
	v_lshl_add_u64 v[32:33], v[32:33], 0, v[142:143]
	v_lshl_add_u64 v[42:43], v[32:33], 2, s[44:45]
	s_waitcnt vmcnt(24)
	v_mov_b32_e32 v34, v160
	v_mov_b32_e32 v35, v161
	v_mov_b32_e32 v36, v162
	v_mov_b32_e32 v37, v163
	v_mov_b32_e32 v38, v164
	v_mov_b32_e32 v39, v165
	v_mov_b32_e32 v40, v166
	v_mov_b32_e32 v41, v167
	v_pk_add_f32 v[26:27], v[26:27], v[36:37]
	v_pk_add_f32 v[30:31], v[30:31], v[40:41]
	v_pk_add_f32 v[28:29], v[28:29], v[38:39]
	v_pk_add_f32 v[24:25], v[24:25], v[34:35]
	global_store_dwordx4 v[42:43], v[28:31], off nt
	global_store_dwordx4 v[42:43], v[24:27], off offset:16 nt
	v_cvt_pk_bf16_f32 v34, v28, v29
	v_mul_f32_e32 v29, v29, v29
	v_fmac_f32_e32 v29, v28, v28
	v_mul_f32_e32 v28, v31, v31
	v_cvt_pk_bf16_f32 v36, v24, v25
	v_fmac_f32_e32 v28, v30, v30
	v_mul_f32_e32 v25, v25, v25
	v_add_f32_e32 v28, v29, v28
	v_fmac_f32_e32 v25, v24, v24
	v_cvt_pk_bf16_f32 v35, v30, v31
	v_cvt_pk_bf16_f32 v37, v26, v27
	v_lshl_add_u64 v[38:39], v[32:33], 1, s[50:51]
	v_add_f32_e32 v24, v28, v25
	v_mul_f32_e32 v25, v27, v27
	v_or_b32_e32 v32, 0x80, v32
	global_store_dwordx4 v[38:39], v[34:37], off
	v_fmac_f32_e32 v25, v26, v26
	s_nop 0
	v_lshl_add_u64 v[34:35], v[32:33], 2, s[44:45]
	v_add_f32_e32 v36, v25, v24
	s_waitcnt vmcnt(22)
	v_mov_b32_e32 v24, v168
	v_mov_b32_e32 v25, v169
	v_mov_b32_e32 v26, v170
	v_mov_b32_e32 v27, v171
	v_mov_b32_e32 v28, v172
	v_mov_b32_e32 v29, v173
	v_mov_b32_e32 v30, v174
	v_mov_b32_e32 v31, v175
	v_pk_add_f32 v[18:19], v[18:19], v[26:27]
	v_pk_add_f32 v[22:23], v[22:23], v[30:31]
	v_pk_add_f32 v[20:21], v[20:21], v[28:29]
	v_pk_add_f32 v[16:17], v[16:17], v[24:25]
	global_store_dwordx4 v[34:35], v[20:23], off nt
	global_store_dwordx4 v[34:35], v[16:19], off offset:16 nt
	v_cvt_pk_bf16_f32 v24, v20, v21
	v_mul_f32_e32 v21, v21, v21
	v_fmac_f32_e32 v21, v20, v20
	v_mul_f32_e32 v20, v23, v23
	v_cvt_pk_bf16_f32 v26, v16, v17
	v_fmac_f32_e32 v20, v22, v22
	v_mul_f32_e32 v17, v17, v17
	v_add_f32_e32 v20, v21, v20
	v_fmac_f32_e32 v17, v16, v16
	v_add_f32_e32 v16, v20, v17
	v_mul_f32_e32 v17, v19, v19
	v_fmac_f32_e32 v17, v18, v18
	v_add_f32_e32 v16, v17, v16
	v_add_f32_e32 v16, v36, v16
	ds_bpermute_b32 v17, v116, v16
	v_cvt_pk_bf16_f32 v25, v22, v23
	v_cvt_pk_bf16_f32 v27, v18, v19
	v_lshl_add_u64 v[28:29], v[32:33], 1, s[50:51]
	global_store_dwordx4 v[28:29], v[24:27], off
	s_waitcnt lgkmcnt(0)
	v_add_f32_e32 v16, v16, v17
	ds_bpermute_b32 v17, v117, v16
	s_and_saveexec_b64 s[14:15], s[46:47]
	s_cbranch_execz .LBB0_1581
	s_waitcnt lgkmcnt(0)
	v_add_f32_e32 v16, v16, v17
	v_mul_f32_e32 v16, 0x4f800000, v16
	v_rndne_f32_e32 v16, v16
	v_mul_f32_e32 v17, 0x2f800000, v16
	v_floor_f32_e32 v17, v17
	v_fmac_f32_e32 v16, 0xcf800000, v17
	v_cvt_u32_f32_e32 v16, v16
	v_cvt_u32_f32_e32 v17, v17
	v_mov_b32_e32 v244, v16
	v_mov_b32_e32 v245, v17
; DI void ss_add(ssacc_t* p, float v) { atomicAdd(p, (ssacc_t)__float2ull_rn(v * 4294967296.f)); }
; DI float quad_sum(float s) { s += __shfl_xor(s, 16); s += __shfl_xor(s, 32); return s; }
; DI float sq8(const f32x4& a, const f32x4& b) { return (a[0] * a[0] + a[1] * a[1]) + (a[2] * a[2] + a[3] * a[3]) + (b[0] * b[0] + b[1] * b[1]) + (b[2] * b[2] + b[3] * b[3]); }
; DI u32x4 pack8(const f32x4& a, const f32x4& b) { u32x4 w; w.x = cvtpk(a[0], a[1]); w.y = cvtpk(a[2], a[3]); w.z = cvtpk(b[0], b[1]); w.w = cvtpk(b[2], b[3]); return w; }
;     DI void operator()(const Acc& acc, const Unit& u, int wr, int wc, int fr, int fq) const {
;     ...
;                 asm volatile("" ::: "memory");
;                 const int row = u.pm * 256 + ai * 128 + wr * 64 + m * 16 + fr;
;                 float sq = 0.f;
; #pragma unroll
;                 for (int bj = 0; bj < 2; ++bj) {
;                     const size_t off = (size_t)row * 2048 + u.pn * 256 + bj * 128 + wc * 32 + 8 * fq;
;                     const f32x4 v0 = *(const f32x4*)(X + off) + acc[ai][bj][m][0], v1 = *(const f32x4*)(X + off + 4) + acc[ai][bj][m][1];
;                     *(f32x4*)(X + off) = v0; *(f32x4*)(X + off + 4) = v1; *(u32x4*)(XB + off) = pack8(v0, v1); sq += sq8(v0, v1);
;                 }
;                 sq = quad_sum(sq); if (fq == 0) ss_add(ssx + row, sq);
.LBB0_1581:
	s_or_b64 exec, exec, s[14:15]
	v_add_u32_e32 v16, 0xb0, v144
	s_waitcnt lgkmcnt(0)
	v_ashrrev_i32_e32 v17, 31, v16
	v_lshlrev_b64 v[16:17], 11, v[16:17]
	v_lshl_add_u64 v[16:17], v[16:17], 0, v[142:143]
	v_lshl_add_u64 v[26:27], v[16:17], 2, s[44:45]
	s_waitcnt vmcnt(20)
	v_mov_b32_e32 v18, v176
	v_mov_b32_e32 v19, v177
	v_mov_b32_e32 v20, v178
	v_mov_b32_e32 v21, v179
	v_mov_b32_e32 v22, v180
	v_mov_b32_e32 v23, v181
	v_mov_b32_e32 v24, v182
	v_mov_b32_e32 v25, v183
	v_pk_add_f32 v[10:11], v[10:11], v[20:21]
	v_pk_add_f32 v[14:15], v[14:15], v[24:25]
	v_pk_add_f32 v[12:13], v[12:13], v[22:23]
	v_pk_add_f32 v[8:9], v[8:9], v[18:19]
	global_store_dwordx4 v[26:27], v[12:15], off nt
	global_store_dwordx4 v[26:27], v[8:11], off offset:16 nt
	v_cvt_pk_bf16_f32 v18, v12, v13
	v_mul_f32_e32 v13, v13, v13
	v_fmac_f32_e32 v13, v12, v12
	v_mul_f32_e32 v12, v15, v15
	v_cvt_pk_bf16_f32 v20, v8, v9
	v_fmac_f32_e32 v12, v14, v14
	v_mul_f32_e32 v9, v9, v9
	v_add_f32_e32 v12, v13, v12
	v_fmac_f32_e32 v9, v8, v8
	v_cvt_pk_bf16_f32 v19, v14, v15
	v_cvt_pk_bf16_f32 v21, v10, v11
	v_lshl_add_u64 v[22:23], v[16:17], 1, s[50:51]
	v_add_f32_e32 v8, v12, v9
	v_mul_f32_e32 v9, v11, v11
	v_or_b32_e32 v16, 0x80, v16
	global_store_dwordx4 v[22:23], v[18:21], off
	v_fmac_f32_e32 v9, v10, v10
	s_nop 0
	v_lshl_add_u64 v[18:19], v[16:17], 2, s[44:45]
	v_add_f32_e32 v20, v9, v8
	s_waitcnt vmcnt(18)
	v_mov_b32_e32 v8, v208
	v_mov_b32_e32 v9, v209
	v_mov_b32_e32 v10, v210
	v_mov_b32_e32 v11, v211
	v_mov_b32_e32 v12, v212
	v_mov_b32_e32 v13, v213
	v_mov_b32_e32 v14, v214
	v_mov_b32_e32 v15, v215
	v_pk_add_f32 v[2:3], v[2:3], v[10:11]
	v_pk_add_f32 v[6:7], v[6:7], v[14:15]
	v_pk_add_f32 v[4:5], v[4:5], v[12:13]
	v_pk_add_f32 v[0:1], v[0:1], v[8:9]
	global_store_dwordx4 v[18:19], v[4:7], off nt
	global_store_dwordx4 v[18:19], v[0:3], off offset:16 nt
	v_cvt_pk_bf16_f32 v8, v4, v5
	v_mul_f32_e32 v5, v5, v5
	v_fmac_f32_e32 v5, v4, v4
	v_mul_f32_e32 v4, v7, v7
	v_cvt_pk_bf16_f32 v10, v0, v1
	v_fmac_f32_e32 v4, v6, v6
	v_mul_f32_e32 v1, v1, v1
	v_add_f32_e32 v4, v5, v4
	v_fmac_f32_e32 v1, v0, v0
	v_add_f32_e32 v0, v4, v1
	v_mul_f32_e32 v1, v3, v3
	v_fmac_f32_e32 v1, v2, v2
	v_add_f32_e32 v0, v1, v0
	v_add_f32_e32 v0, v20, v0
	ds_bpermute_b32 v1, v116, v0
	v_cvt_pk_bf16_f32 v9, v6, v7
	v_cvt_pk_bf16_f32 v11, v2, v3
	v_lshl_add_u64 v[12:13], v[16:17], 1, s[50:51]
	global_store_dwordx4 v[12:13], v[8:11], off
	s_waitcnt lgkmcnt(0)
	v_add_f32_e32 v0, v0, v1
	ds_bpermute_b32 v1, v117, v0
	s_and_saveexec_b64 s[14:15], s[46:47]
	s_cbranch_execz .LBB0_1583
	s_waitcnt lgkmcnt(0)
	v_add_f32_e32 v0, v0, v1
	v_mul_f32_e32 v0, 0x4f800000, v0
	v_rndne_f32_e32 v0, v0
	v_mul_f32_e32 v1, 0x2f800000, v0
	v_floor_f32_e32 v1, v1
	v_fmac_f32_e32 v0, 0xcf800000, v1
	v_cvt_u32_f32_e32 v0, v0
	v_cvt_u32_f32_e32 v1, v1
	global_atomic_add_x2 v[112:113], v[232:233], off
	global_atomic_add_x2 v[112:113], v[234:235], off offset:128
	global_atomic_add_x2 v[112:113], v[236:237], off offset:256
	global_atomic_add_x2 v[112:113], v[238:239], off offset:384
	global_atomic_add_x2 v[112:113], v[240:241], off offset:1024
	global_atomic_add_x2 v[112:113], v[242:243], off offset:1152
	global_atomic_add_x2 v[112:113], v[244:245], off offset:1280
	global_atomic_add_x2 v[112:113], v[0:1], off offset:1408
